# attention step: max/decision/DMA folded into PV MFMA gaps; fewer waitcnt/nop; decision via vcc
# speedup vs baseline: 1.1467x; 1.0082x over previous
.Lat_mainloop:
.Lat_step_M1:
	v_add_u32_e32 v243, s16, v204
	ds_read_b64_tr_b16 v[214:215], v243 offset:24576
	ds_read_b64_tr_b16 v[216:217], v243 offset:25088
	v_mfma_f32_32x32x16_bf16 v[112:127], v[176:179], v[144:147], v[64:79]
	v_add_f32_e32 v245, v80, v81
	v_add_f32_e32 v245, v82, v245
	v_add_f32_e32 v245, v83, v245
	v_add_f32_e32 v245, v84, v245
	v_add_f32_e32 v245, v85, v245
	v_cvt_pk_bf16_f32 v160, v80, v81
	v_cvt_pk_bf16_f32 v161, v82, v83
	ds_read_b64_tr_b16 v[80:81], v243 offset:28672
	ds_read_b64_tr_b16 v[82:83], v243 offset:29184
	v_mfma_f32_32x32x16_bf16 v[128:143], v[180:183], v[144:147], v[64:79]
	v_add_f32_e32 v245, v86, v245
	v_add_f32_e32 v245, v87, v245
	v_add_f32_e32 v245, v88, v245
	v_add_f32_e32 v245, v89, v245
	v_cvt_pk_bf16_f32 v162, v84, v85
	v_cvt_pk_bf16_f32 v163, v86, v87
	ds_read_b64_tr_b16 v[84:85], v243 offset:25600
	ds_read_b64_tr_b16 v[86:87], v243 offset:26112
	v_mfma_f32_32x32x16_bf16 v[112:127], v[184:187], v[148:151], v[112:127]
	v_add_f32_e32 v245, v90, v245
	v_add_f32_e32 v245, v91, v245
	v_add_f32_e32 v245, v92, v245
	v_add_f32_e32 v245, v93, v245
	v_cvt_pk_bf16_f32 v164, v88, v89
	v_cvt_pk_bf16_f32 v165, v90, v91
	ds_read_b64_tr_b16 v[88:89], v243 offset:29696
	ds_read_b64_tr_b16 v[90:91], v243 offset:30208
	v_mfma_f32_32x32x16_bf16 v[128:143], v[188:191], v[148:151], v[128:143]
	v_add_f32_e32 v245, v94, v245
	v_add_f32_e32 v245, v95, v245
	v_add_f32_e32 v245, v96, v245
	v_add_f32_e32 v245, v97, v245
	v_cvt_pk_bf16_f32 v166, v92, v93
	v_cvt_pk_bf16_f32 v167, v94, v95
	ds_read_b64_tr_b16 v[92:93], v243 offset:26624
	ds_read_b64_tr_b16 v[94:95], v243 offset:27136
	v_mfma_f32_32x32x16_bf16 v[112:127], v[192:195], v[152:155], v[112:127]
	v_add_f32_e32 v245, v98, v245
	v_add_f32_e32 v245, v99, v245
	v_add_f32_e32 v245, v100, v245
	v_add_f32_e32 v245, v101, v245
	v_cvt_pk_bf16_f32 v168, v96, v97
	v_cvt_pk_bf16_f32 v169, v98, v99
	ds_read_b64_tr_b16 v[96:97], v243 offset:30720
	ds_read_b64_tr_b16 v[98:99], v243 offset:31232
	v_mfma_f32_32x32x16_bf16 v[128:143], v[196:199], v[152:155], v[128:143]
	v_add_f32_e32 v245, v102, v245
	v_add_f32_e32 v245, v103, v245
	v_add_f32_e32 v245, v104, v245
	v_add_f32_e32 v245, v105, v245
	v_cvt_pk_bf16_f32 v170, v100, v101
	v_cvt_pk_bf16_f32 v171, v102, v103
	ds_read_b64_tr_b16 v[100:101], v243 offset:27648
	ds_read_b64_tr_b16 v[102:103], v243 offset:28160
	v_mfma_f32_32x32x16_bf16 v[112:127], v[200:203], v[156:159], v[112:127]
	v_add_f32_e32 v245, v106, v245
	v_add_f32_e32 v245, v107, v245
	v_add_f32_e32 v245, v108, v245
	v_add_f32_e32 v245, v109, v245
	v_cvt_pk_bf16_f32 v172, v104, v105
	v_cvt_pk_bf16_f32 v173, v106, v107
	ds_read_b64_tr_b16 v[104:105], v243 offset:31744
	ds_read_b64_tr_b16 v[106:107], v243 offset:32256
	v_mfma_f32_32x32x16_bf16 v[128:143], v[206:209], v[156:159], v[128:143]
	v_add_f32_e32 v245, v110, v245
	v_add_f32_e32 v245, v111, v245
	v_cvt_pk_bf16_f32 v174, v108, v109
	v_cvt_pk_bf16_f32 v175, v110, v111
	v_add_f32_e32 v211, v211, v245
	v_add_u32_e32 v244, s18, v219
	s_waitcnt lgkmcnt(8)
	v_mfma_f32_32x32x16_bf16 v[0:15], v[160:163], v[214:217], v[0:15]
	v_max3_f32 v246, v112, v113, v114
	v_max3_f32 v247, v115, v116, v117
	ds_read_b64_tr_b16 v[214:215], v243 offset:49152
	ds_read_b64_tr_b16 v[216:217], v243 offset:49664
	v_mfma_f32_32x32x16_bf16 v[16:31], v[160:163], v[80:83], v[16:31]
	s_add_i32 m0, s17, s54
	v_max3_f32 v246, v246, v118, v119
	v_max3_f32 v247, v247, v120, v121
	v_max3_f32 v246, v246, v122, v123
	v_max3_f32 v247, v247, v124, v125
	ds_read_b64_tr_b16 v[80:81], v243 offset:53248
	ds_read_b64_tr_b16 v[82:83], v243 offset:53760
	global_load_lds_dwordx4 v222, s[0:1]
	s_add_u32 s0, s0, 0x20000
	s_addc_u32 s1, s1, 0
	v_mfma_f32_32x32x16_bf16 v[0:15], v[164:167], v[84:87], v[0:15]
	s_add_i32 s21, s18, s54
	s_add_i32 m0, s21, 0x6000
	v_max3_f32 v246, v246, v126, v127
	v_max3_f32 v247, v247, v128, v129
	v_max3_f32 v246, v246, v130, v131
	v_max3_f32 v247, v247, v132, v133
	ds_read_b64_tr_b16 v[84:85], v243 offset:50176
	ds_read_b64_tr_b16 v[86:87], v243 offset:50688
	global_load_lds_dwordx4 v223, s[4:5]
	v_mfma_f32_32x32x16_bf16 v[16:31], v[164:167], v[88:91], v[16:31]
	s_add_i32 m0, s21, 0xc000
	v_max3_f32 v246, v246, v134, v135
	v_max3_f32 v247, v247, v136, v137
	v_max3_f32 v246, v246, v138, v139
	v_max3_f32 v247, v247, v140, v141
	ds_read_b64_tr_b16 v[88:89], v243 offset:54272
	ds_read_b64_tr_b16 v[90:91], v243 offset:54784
	global_load_lds_dwordx4 v224, s[4:5]
	s_add_u32 s4, s4, 0x20000
	s_addc_u32 s5, s5, 0
	s_waitcnt lgkmcnt(8)
	v_mfma_f32_32x32x16_bf16 v[0:15], v[168:171], v[92:95], v[0:15]
	v_max3_f32 v246, v246, v142, v143
	v_max_f32_e32 v248, v246, v247
	v_mov_b32_e32 v246, v248
	ds_read_b64_tr_b16 v[92:93], v243 offset:51200
	ds_read_b64_tr_b16 v[94:95], v243 offset:51712
	v_permlane32_swap_b32_e32 v248, v246
	v_max_f32_e32 v248, v248, v246
	v_cmp_lt_f32_e32 vcc, s87, v248
	s_cbranch_vccnz .Lat_rare_M1
.Lat_cont_M1:
	v_mfma_f32_32x32x16_bf16 v[16:31], v[168:171], v[96:99], v[16:31]
	v_exp_f32_e32 v112, v112
	v_exp_f32_e32 v113, v113
	v_exp_f32_e32 v114, v114
	ds_read_b64_tr_b16 v[96:97], v243 offset:55296
	ds_read_b64_tr_b16 v[98:99], v243 offset:55808
	v_mfma_f32_32x32x16_bf16 v[0:15], v[172:175], v[100:103], v[0:15]
	v_exp_f32_e32 v115, v115
	v_exp_f32_e32 v116, v116
	v_exp_f32_e32 v117, v117
	ds_read_b64_tr_b16 v[100:101], v243 offset:52224
	ds_read_b64_tr_b16 v[102:103], v243 offset:52736
	v_mfma_f32_32x32x16_bf16 v[16:31], v[172:175], v[104:107], v[16:31]
	v_exp_f32_e32 v118, v118
	v_exp_f32_e32 v119, v119
	v_exp_f32_e32 v120, v120
	ds_read_b64_tr_b16 v[104:105], v243 offset:56320
	ds_read_b64_tr_b16 v[106:107], v243 offset:56832
	s_waitcnt lgkmcnt(8)
	v_mfma_f32_32x32x16_bf16 v[32:47], v[160:163], v[214:217], v[32:47]
	v_exp_f32_e32 v121, v121
	v_exp_f32_e32 v122, v122
	v_exp_f32_e32 v123, v123
	ds_read_b128 v[176:179], v244 offset:0
	ds_read_b128 v[180:183], v244 offset:512
	v_mfma_f32_32x32x16_bf16 v[48:63], v[160:163], v[80:83], v[48:63]
	v_exp_f32_e32 v124, v124
	v_exp_f32_e32 v125, v125
	v_exp_f32_e32 v126, v126
	ds_read_b128 v[184:187], v244 offset:2048
	ds_read_b128 v[188:191], v244 offset:2560
	v_mfma_f32_32x32x16_bf16 v[32:47], v[164:167], v[84:87], v[32:47]
	v_exp_f32_e32 v127, v127
	v_exp_f32_e32 v128, v128
	v_exp_f32_e32 v129, v129
	ds_read_b128 v[192:195], v244 offset:4096
	ds_read_b128 v[196:199], v244 offset:4608
	v_mfma_f32_32x32x16_bf16 v[48:63], v[164:167], v[88:91], v[48:63]
	v_exp_f32_e32 v130, v130
	v_exp_f32_e32 v131, v131
	v_exp_f32_e32 v132, v132
	ds_read_b128 v[200:203], v244 offset:6144
	ds_read_b128 v[206:209], v244 offset:6656
	s_waitcnt lgkmcnt(8)
	v_mfma_f32_32x32x16_bf16 v[32:47], v[168:171], v[92:95], v[32:47]
	v_exp_f32_e32 v133, v133
	v_exp_f32_e32 v134, v134
	v_exp_f32_e32 v135, v135
	v_mfma_f32_32x32x16_bf16 v[48:63], v[168:171], v[96:99], v[48:63]
	v_exp_f32_e32 v136, v136
	v_exp_f32_e32 v137, v137
	v_exp_f32_e32 v138, v138
	v_mfma_f32_32x32x16_bf16 v[32:47], v[172:175], v[100:103], v[32:47]
	v_exp_f32_e32 v139, v139
	v_exp_f32_e32 v140, v140
	v_exp_f32_e32 v141, v141
	v_mfma_f32_32x32x16_bf16 v[48:63], v[172:175], v[104:107], v[48:63]
	v_exp_f32_e32 v142, v142
	v_exp_f32_e32 v143, v143
	s_waitcnt vmcnt(3) lgkmcnt(0)
	s_barrier
	s_cbranch_vccz .Lat_noresc_M1
	s_waitcnt lgkmcnt(0)
	ds_read_b128 v[214:217], v227 offset:0
	s_waitcnt lgkmcnt(0)
	v_pk_mul_f32 v[0:1], v[0:1], v[214:215]
	v_pk_mul_f32 v[2:3], v[2:3], v[216:217]
	v_pk_mul_f32 v[16:17], v[16:17], v[214:215]
	v_pk_mul_f32 v[18:19], v[18:19], v[216:217]
	v_pk_mul_f32 v[32:33], v[32:33], v[214:215]
	v_pk_mul_f32 v[34:35], v[34:35], v[216:217]
	v_pk_mul_f32 v[48:49], v[48:49], v[214:215]
	v_pk_mul_f32 v[50:51], v[50:51], v[216:217]
	ds_read_b128 v[214:217], v227 offset:32
	s_waitcnt lgkmcnt(0)
	v_pk_mul_f32 v[4:5], v[4:5], v[214:215]
	v_pk_mul_f32 v[6:7], v[6:7], v[216:217]
	v_pk_mul_f32 v[20:21], v[20:21], v[214:215]
	v_pk_mul_f32 v[22:23], v[22:23], v[216:217]
	v_pk_mul_f32 v[36:37], v[36:37], v[214:215]
	v_pk_mul_f32 v[38:39], v[38:39], v[216:217]
	v_pk_mul_f32 v[52:53], v[52:53], v[214:215]
	v_pk_mul_f32 v[54:55], v[54:55], v[216:217]
	ds_read_b128 v[214:217], v227 offset:64
	s_waitcnt lgkmcnt(0)
	v_pk_mul_f32 v[8:9], v[8:9], v[214:215]
	v_pk_mul_f32 v[10:11], v[10:11], v[216:217]
	v_pk_mul_f32 v[24:25], v[24:25], v[214:215]
	v_pk_mul_f32 v[26:27], v[26:27], v[216:217]
	v_pk_mul_f32 v[40:41], v[40:41], v[214:215]
	v_pk_mul_f32 v[42:43], v[42:43], v[216:217]
	v_pk_mul_f32 v[56:57], v[56:57], v[214:215]
	v_pk_mul_f32 v[58:59], v[58:59], v[216:217]
	ds_read_b128 v[214:217], v227 offset:96
	s_waitcnt lgkmcnt(0)
	v_pk_mul_f32 v[12:13], v[12:13], v[214:215]
	v_pk_mul_f32 v[14:15], v[14:15], v[216:217]
	v_pk_mul_f32 v[28:29], v[28:29], v[214:215]
	v_pk_mul_f32 v[30:31], v[30:31], v[216:217]
	v_pk_mul_f32 v[44:45], v[44:45], v[214:215]
	v_pk_mul_f32 v[46:47], v[46:47], v[216:217]
	v_pk_mul_f32 v[60:61], v[60:61], v[214:215]
	v_pk_mul_f32 v[62:63], v[62:63], v[216:217]

.Lat_step_M2:
	v_add_u32_e32 v243, s16, v204
	ds_read_b64_tr_b16 v[214:215], v243 offset:24576
	ds_read_b64_tr_b16 v[216:217], v243 offset:25088
	v_mfma_f32_32x32x16_bf16 v[80:95], v[176:179], v[144:147], v[64:79]
	v_add_f32_e32 v245, v112, v113
	v_add_f32_e32 v245, v114, v245
	v_add_f32_e32 v245, v115, v245
	v_add_f32_e32 v245, v116, v245
	v_add_f32_e32 v245, v117, v245
	v_cvt_pk_bf16_f32 v160, v112, v113
	v_cvt_pk_bf16_f32 v161, v114, v115
	ds_read_b64_tr_b16 v[112:113], v243 offset:28672
	ds_read_b64_tr_b16 v[114:115], v243 offset:29184
	v_mfma_f32_32x32x16_bf16 v[96:111], v[180:183], v[144:147], v[64:79]
	v_add_f32_e32 v245, v118, v245
	v_add_f32_e32 v245, v119, v245
	v_add_f32_e32 v245, v120, v245
	v_add_f32_e32 v245, v121, v245
	v_cvt_pk_bf16_f32 v162, v116, v117
	v_cvt_pk_bf16_f32 v163, v118, v119
	ds_read_b64_tr_b16 v[116:117], v243 offset:25600
	ds_read_b64_tr_b16 v[118:119], v243 offset:26112
	v_mfma_f32_32x32x16_bf16 v[80:95], v[184:187], v[148:151], v[80:95]
	v_add_f32_e32 v245, v122, v245
	v_add_f32_e32 v245, v123, v245
	v_add_f32_e32 v245, v124, v245
	v_add_f32_e32 v245, v125, v245
	v_cvt_pk_bf16_f32 v164, v120, v121
	v_cvt_pk_bf16_f32 v165, v122, v123
	ds_read_b64_tr_b16 v[120:121], v243 offset:29696
	ds_read_b64_tr_b16 v[122:123], v243 offset:30208
	v_mfma_f32_32x32x16_bf16 v[96:111], v[188:191], v[148:151], v[96:111]
	v_add_f32_e32 v245, v126, v245
	v_add_f32_e32 v245, v127, v245
	v_add_f32_e32 v245, v128, v245
	v_add_f32_e32 v245, v129, v245
	v_cvt_pk_bf16_f32 v166, v124, v125
	v_cvt_pk_bf16_f32 v167, v126, v127
	ds_read_b64_tr_b16 v[124:125], v243 offset:26624
	ds_read_b64_tr_b16 v[126:127], v243 offset:27136
	v_mfma_f32_32x32x16_bf16 v[80:95], v[192:195], v[152:155], v[80:95]
	v_add_f32_e32 v245, v130, v245
	v_add_f32_e32 v245, v131, v245
	v_add_f32_e32 v245, v132, v245
	v_add_f32_e32 v245, v133, v245
	v_cvt_pk_bf16_f32 v168, v128, v129
	v_cvt_pk_bf16_f32 v169, v130, v131
	ds_read_b64_tr_b16 v[128:129], v243 offset:30720
	ds_read_b64_tr_b16 v[130:131], v243 offset:31232
	v_mfma_f32_32x32x16_bf16 v[96:111], v[196:199], v[152:155], v[96:111]
	v_add_f32_e32 v245, v134, v245
	v_add_f32_e32 v245, v135, v245
	v_add_f32_e32 v245, v136, v245
	v_add_f32_e32 v245, v137, v245
	v_cvt_pk_bf16_f32 v170, v132, v133
	v_cvt_pk_bf16_f32 v171, v134, v135
	ds_read_b64_tr_b16 v[132:133], v243 offset:27648
	ds_read_b64_tr_b16 v[134:135], v243 offset:28160
	v_mfma_f32_32x32x16_bf16 v[80:95], v[200:203], v[156:159], v[80:95]
	v_add_f32_e32 v245, v138, v245
	v_add_f32_e32 v245, v139, v245
	v_add_f32_e32 v245, v140, v245
	v_add_f32_e32 v245, v141, v245
	v_cvt_pk_bf16_f32 v172, v136, v137
	v_cvt_pk_bf16_f32 v173, v138, v139
	ds_read_b64_tr_b16 v[136:137], v243 offset:31744
	ds_read_b64_tr_b16 v[138:139], v243 offset:32256
	v_mfma_f32_32x32x16_bf16 v[96:111], v[206:209], v[156:159], v[96:111]
	v_add_f32_e32 v245, v142, v245
	v_add_f32_e32 v245, v143, v245
	v_cvt_pk_bf16_f32 v174, v140, v141
	v_cvt_pk_bf16_f32 v175, v142, v143
	v_add_f32_e32 v211, v211, v245
	v_add_u32_e32 v244, s18, v219
	s_waitcnt lgkmcnt(8)
	v_mfma_f32_32x32x16_bf16 v[0:15], v[160:163], v[214:217], v[0:15]
	v_max3_f32 v246, v80, v81, v82
	v_max3_f32 v247, v83, v84, v85
	ds_read_b64_tr_b16 v[214:215], v243 offset:49152
	ds_read_b64_tr_b16 v[216:217], v243 offset:49664
	v_mfma_f32_32x32x16_bf16 v[16:31], v[160:163], v[112:115], v[16:31]
	s_add_i32 m0, s17, s54
	v_max3_f32 v246, v246, v86, v87
	v_max3_f32 v247, v247, v88, v89
	v_max3_f32 v246, v246, v90, v91
	v_max3_f32 v247, v247, v92, v93
	ds_read_b64_tr_b16 v[112:113], v243 offset:53248
	ds_read_b64_tr_b16 v[114:115], v243 offset:53760
	global_load_lds_dwordx4 v222, s[0:1]
	s_add_u32 s0, s0, 0x20000
	s_addc_u32 s1, s1, 0
	v_mfma_f32_32x32x16_bf16 v[0:15], v[164:167], v[116:119], v[0:15]
	s_add_i32 s21, s18, s54
	s_add_i32 m0, s21, 0x6000
	v_max3_f32 v246, v246, v94, v95
	v_max3_f32 v247, v247, v96, v97
	v_max3_f32 v246, v246, v98, v99
	v_max3_f32 v247, v247, v100, v101
	ds_read_b64_tr_b16 v[116:117], v243 offset:50176
	ds_read_b64_tr_b16 v[118:119], v243 offset:50688
	global_load_lds_dwordx4 v223, s[4:5]
	v_mfma_f32_32x32x16_bf16 v[16:31], v[164:167], v[120:123], v[16:31]
	s_add_i32 m0, s21, 0xc000
	v_max3_f32 v246, v246, v102, v103
	v_max3_f32 v247, v247, v104, v105
	v_max3_f32 v246, v246, v106, v107
	v_max3_f32 v247, v247, v108, v109
	ds_read_b64_tr_b16 v[120:121], v243 offset:54272
	ds_read_b64_tr_b16 v[122:123], v243 offset:54784
	global_load_lds_dwordx4 v224, s[4:5]
	s_add_u32 s4, s4, 0x20000
	s_addc_u32 s5, s5, 0
	s_waitcnt lgkmcnt(8)
	v_mfma_f32_32x32x16_bf16 v[0:15], v[168:171], v[124:127], v[0:15]
	v_max3_f32 v246, v246, v110, v111
	v_max_f32_e32 v248, v246, v247
	v_mov_b32_e32 v246, v248
	ds_read_b64_tr_b16 v[124:125], v243 offset:51200
	ds_read_b64_tr_b16 v[126:127], v243 offset:51712
	v_permlane32_swap_b32_e32 v248, v246
	v_max_f32_e32 v248, v248, v246
	v_cmp_lt_f32_e32 vcc, s87, v248
	s_cbranch_vccnz .Lat_rare_M2
; #define WAIT_BAR(N) asm volatile("s_waitcnt vmcnt(" #N ") lgkmcnt(0)\n\ts_barrier":::"memory")
;   #define RESC() do{ if(resc){ asm volatile("s_waitcnt lgkmcnt(0)":::"memory"); \
;       _Pragma("unroll") for(int d_=0;d_<2;++d_) _Pragma("unroll") for(int r=0;r<16;++r)o[d_][r]*=wsf[crow(r,hi)]; } }while(0)
;   #define ROT() do{sl_prev=sl_cur;sl_cur=sl_next;sl_next=(sl_next==(NSLOT-1)*SLOTB)?0:sl_next+SLOTB;}while(0)
; template<int THRL> __device__ __forceinline__ void attn_unit(int b,int qc,int vc,int qb,const bf16*Q,const bf16*__restrict__ K,const bf16*__restrict__ V,bf16*O,char*shm,const int tid){
;     ...
;   int t=1;
;     ...
;   for(;t+5<NT;t+=2){
;     STEP(pB0,pB1,pA0,pA1,t,true,true,true);     WAIT_BAR(2); RESC(); ROT();
;     STEP(pA0,pA1,pB0,pB1,t+1,true,true,true);   WAIT_BAR(2); RESC(); ROT();
.Lat_cont_M2:
	v_mfma_f32_32x32x16_bf16 v[16:31], v[168:171], v[128:131], v[16:31]
	v_exp_f32_e32 v80, v80
	v_exp_f32_e32 v81, v81
	v_exp_f32_e32 v82, v82
	ds_read_b64_tr_b16 v[128:129], v243 offset:55296
	ds_read_b64_tr_b16 v[130:131], v243 offset:55808
	v_mfma_f32_32x32x16_bf16 v[0:15], v[172:175], v[132:135], v[0:15]
	v_exp_f32_e32 v83, v83
	v_exp_f32_e32 v84, v84
	v_exp_f32_e32 v85, v85
	ds_read_b64_tr_b16 v[132:133], v243 offset:52224
	ds_read_b64_tr_b16 v[134:135], v243 offset:52736
	v_mfma_f32_32x32x16_bf16 v[16:31], v[172:175], v[136:139], v[16:31]
	v_exp_f32_e32 v86, v86
	v_exp_f32_e32 v87, v87
	v_exp_f32_e32 v88, v88
	ds_read_b64_tr_b16 v[136:137], v243 offset:56320
	ds_read_b64_tr_b16 v[138:139], v243 offset:56832
	s_waitcnt lgkmcnt(8)
	v_mfma_f32_32x32x16_bf16 v[32:47], v[160:163], v[214:217], v[32:47]
	v_exp_f32_e32 v89, v89
	v_exp_f32_e32 v90, v90
	v_exp_f32_e32 v91, v91
	ds_read_b128 v[176:179], v244 offset:0
	ds_read_b128 v[180:183], v244 offset:512
	v_mfma_f32_32x32x16_bf16 v[48:63], v[160:163], v[112:115], v[48:63]
	v_exp_f32_e32 v92, v92
	v_exp_f32_e32 v93, v93
	v_exp_f32_e32 v94, v94
	ds_read_b128 v[184:187], v244 offset:2048
	ds_read_b128 v[188:191], v244 offset:2560
	v_mfma_f32_32x32x16_bf16 v[32:47], v[164:167], v[116:119], v[32:47]
	v_exp_f32_e32 v95, v95
	v_exp_f32_e32 v96, v96
	v_exp_f32_e32 v97, v97
	ds_read_b128 v[192:195], v244 offset:4096
	ds_read_b128 v[196:199], v244 offset:4608
	v_mfma_f32_32x32x16_bf16 v[48:63], v[164:167], v[120:123], v[48:63]
	v_exp_f32_e32 v98, v98
	v_exp_f32_e32 v99, v99
	v_exp_f32_e32 v100, v100
	ds_read_b128 v[200:203], v244 offset:6144
	ds_read_b128 v[206:209], v244 offset:6656
	s_waitcnt lgkmcnt(8)
	v_mfma_f32_32x32x16_bf16 v[32:47], v[168:171], v[124:127], v[32:47]
	v_exp_f32_e32 v101, v101
	v_exp_f32_e32 v102, v102
	v_exp_f32_e32 v103, v103
	v_mfma_f32_32x32x16_bf16 v[48:63], v[168:171], v[128:131], v[48:63]
	v_exp_f32_e32 v104, v104
	v_exp_f32_e32 v105, v105
	v_exp_f32_e32 v106, v106
	v_mfma_f32_32x32x16_bf16 v[32:47], v[172:175], v[132:135], v[32:47]
	v_exp_f32_e32 v107, v107
	v_exp_f32_e32 v108, v108
	v_exp_f32_e32 v109, v109
	v_mfma_f32_32x32x16_bf16 v[48:63], v[172:175], v[136:139], v[48:63]
	v_exp_f32_e32 v110, v110
	v_exp_f32_e32 v111, v111
	s_waitcnt vmcnt(3) lgkmcnt(0)
	s_barrier
	s_cbranch_vccz .Lat_noresc_M2
	s_waitcnt lgkmcnt(0)
	ds_read_b128 v[214:217], v227 offset:0
	s_waitcnt lgkmcnt(0)
	v_pk_mul_f32 v[0:1], v[0:1], v[214:215]
	v_pk_mul_f32 v[2:3], v[2:3], v[216:217]
	v_pk_mul_f32 v[16:17], v[16:17], v[214:215]
	v_pk_mul_f32 v[18:19], v[18:19], v[216:217]
	v_pk_mul_f32 v[32:33], v[32:33], v[214:215]
	v_pk_mul_f32 v[34:35], v[34:35], v[216:217]
	v_pk_mul_f32 v[48:49], v[48:49], v[214:215]
	v_pk_mul_f32 v[50:51], v[50:51], v[216:217]
	ds_read_b128 v[214:217], v227 offset:32
	s_waitcnt lgkmcnt(0)
	v_pk_mul_f32 v[4:5], v[4:5], v[214:215]
	v_pk_mul_f32 v[6:7], v[6:7], v[216:217]
	v_pk_mul_f32 v[20:21], v[20:21], v[214:215]
	v_pk_mul_f32 v[22:23], v[22:23], v[216:217]
	v_pk_mul_f32 v[36:37], v[36:37], v[214:215]
	v_pk_mul_f32 v[38:39], v[38:39], v[216:217]
	v_pk_mul_f32 v[52:53], v[52:53], v[214:215]
	v_pk_mul_f32 v[54:55], v[54:55], v[216:217]
	ds_read_b128 v[214:217], v227 offset:64
	s_waitcnt lgkmcnt(0)
	v_pk_mul_f32 v[8:9], v[8:9], v[214:215]
	v_pk_mul_f32 v[10:11], v[10:11], v[216:217]
	v_pk_mul_f32 v[24:25], v[24:25], v[214:215]
	v_pk_mul_f32 v[26:27], v[26:27], v[216:217]
	v_pk_mul_f32 v[40:41], v[40:41], v[214:215]
	v_pk_mul_f32 v[42:43], v[42:43], v[216:217]
	v_pk_mul_f32 v[56:57], v[56:57], v[214:215]
	v_pk_mul_f32 v[58:59], v[58:59], v[216:217]
	ds_read_b128 v[214:217], v227 offset:96
	s_waitcnt lgkmcnt(0)
	v_pk_mul_f32 v[12:13], v[12:13], v[214:215]
	v_pk_mul_f32 v[14:15], v[14:15], v[216:217]
	v_pk_mul_f32 v[28:29], v[28:29], v[214:215]
	v_pk_mul_f32 v[30:31], v[30:31], v[216:217]
	v_pk_mul_f32 v[44:45], v[44:45], v[214:215]
	v_pk_mul_f32 v[46:47], v[46:47], v[216:217]
	v_pk_mul_f32 v[60:61], v[60:61], v[214:215]
	v_pk_mul_f32 v[62:63], v[62:63], v[216:217]

.Lat_step_T5:
	v_add_u32_e32 v243, s16, v204
	ds_read_b64_tr_b16 v[214:215], v243 offset:24576
	ds_read_b64_tr_b16 v[216:217], v243 offset:25088
	v_mfma_f32_32x32x16_bf16 v[112:127], v[176:179], v[144:147], v[64:79]
	v_add_f32_e32 v245, v80, v81
	v_add_f32_e32 v245, v82, v245
	v_add_f32_e32 v245, v83, v245
	v_add_f32_e32 v245, v84, v245
	v_add_f32_e32 v245, v85, v245
	v_cvt_pk_bf16_f32 v160, v80, v81
	v_cvt_pk_bf16_f32 v161, v82, v83
	ds_read_b64_tr_b16 v[80:81], v243 offset:28672
	ds_read_b64_tr_b16 v[82:83], v243 offset:29184
	v_mfma_f32_32x32x16_bf16 v[128:143], v[180:183], v[144:147], v[64:79]
	v_add_f32_e32 v245, v86, v245
	v_add_f32_e32 v245, v87, v245
	v_add_f32_e32 v245, v88, v245
	v_add_f32_e32 v245, v89, v245
	v_cvt_pk_bf16_f32 v162, v84, v85
	v_cvt_pk_bf16_f32 v163, v86, v87
	ds_read_b64_tr_b16 v[84:85], v243 offset:25600
	ds_read_b64_tr_b16 v[86:87], v243 offset:26112
	v_mfma_f32_32x32x16_bf16 v[112:127], v[184:187], v[148:151], v[112:127]
	v_add_f32_e32 v245, v90, v245
	v_add_f32_e32 v245, v91, v245
	v_add_f32_e32 v245, v92, v245
	v_add_f32_e32 v245, v93, v245
	v_cvt_pk_bf16_f32 v164, v88, v89
	v_cvt_pk_bf16_f32 v165, v90, v91
	ds_read_b64_tr_b16 v[88:89], v243 offset:29696
	ds_read_b64_tr_b16 v[90:91], v243 offset:30208
	v_mfma_f32_32x32x16_bf16 v[128:143], v[188:191], v[148:151], v[128:143]
	v_add_f32_e32 v245, v94, v245
	v_add_f32_e32 v245, v95, v245
	v_add_f32_e32 v245, v96, v245
	v_add_f32_e32 v245, v97, v245
	v_cvt_pk_bf16_f32 v166, v92, v93
	v_cvt_pk_bf16_f32 v167, v94, v95
	ds_read_b64_tr_b16 v[92:93], v243 offset:26624
	ds_read_b64_tr_b16 v[94:95], v243 offset:27136
	v_mfma_f32_32x32x16_bf16 v[112:127], v[192:195], v[152:155], v[112:127]
	v_add_f32_e32 v245, v98, v245
	v_add_f32_e32 v245, v99, v245
	v_add_f32_e32 v245, v100, v245
	v_add_f32_e32 v245, v101, v245
	v_cvt_pk_bf16_f32 v168, v96, v97
	v_cvt_pk_bf16_f32 v169, v98, v99
	ds_read_b64_tr_b16 v[96:97], v243 offset:30720
	ds_read_b64_tr_b16 v[98:99], v243 offset:31232
	v_mfma_f32_32x32x16_bf16 v[128:143], v[196:199], v[152:155], v[128:143]
	v_add_f32_e32 v245, v102, v245
	v_add_f32_e32 v245, v103, v245
	v_add_f32_e32 v245, v104, v245
	v_add_f32_e32 v245, v105, v245
	v_cvt_pk_bf16_f32 v170, v100, v101
	v_cvt_pk_bf16_f32 v171, v102, v103
	ds_read_b64_tr_b16 v[100:101], v243 offset:27648
	ds_read_b64_tr_b16 v[102:103], v243 offset:28160
	v_mfma_f32_32x32x16_bf16 v[112:127], v[200:203], v[156:159], v[112:127]
	v_add_f32_e32 v245, v106, v245
	v_add_f32_e32 v245, v107, v245
	v_add_f32_e32 v245, v108, v245
	v_add_f32_e32 v245, v109, v245
	v_cvt_pk_bf16_f32 v172, v104, v105
	v_cvt_pk_bf16_f32 v173, v106, v107
	ds_read_b64_tr_b16 v[104:105], v243 offset:31744
	ds_read_b64_tr_b16 v[106:107], v243 offset:32256
	v_mfma_f32_32x32x16_bf16 v[128:143], v[206:209], v[156:159], v[128:143]
	v_add_f32_e32 v245, v110, v245
	v_add_f32_e32 v245, v111, v245
	v_cvt_pk_bf16_f32 v174, v108, v109
	v_cvt_pk_bf16_f32 v175, v110, v111
	v_add_f32_e32 v211, v211, v245
	v_add_u32_e32 v244, s18, v219
	s_waitcnt lgkmcnt(8)
	v_mfma_f32_32x32x16_bf16 v[0:15], v[160:163], v[214:217], v[0:15]
	v_max3_f32 v246, v112, v113, v114
	v_max3_f32 v247, v115, v116, v117
	ds_read_b64_tr_b16 v[214:215], v243 offset:49152
	ds_read_b64_tr_b16 v[216:217], v243 offset:49664
	v_mfma_f32_32x32x16_bf16 v[16:31], v[160:163], v[80:83], v[16:31]
	s_add_i32 m0, s17, s54
	v_max3_f32 v246, v246, v118, v119
	v_max3_f32 v247, v247, v120, v121
	v_max3_f32 v246, v246, v122, v123
	v_max3_f32 v247, v247, v124, v125
	ds_read_b64_tr_b16 v[80:81], v243 offset:53248
	ds_read_b64_tr_b16 v[82:83], v243 offset:53760
	global_load_lds_dwordx4 v222, s[0:1]
	s_add_u32 s0, s0, 0x20000
	s_addc_u32 s1, s1, 0
	v_mfma_f32_32x32x16_bf16 v[0:15], v[164:167], v[84:87], v[0:15]
	s_add_i32 s21, s18, s54
	s_add_i32 m0, s21, 0x6000
	v_max3_f32 v246, v246, v126, v127
	v_max3_f32 v247, v247, v128, v129
	v_max3_f32 v246, v246, v130, v131
	v_max3_f32 v247, v247, v132, v133
	ds_read_b64_tr_b16 v[84:85], v243 offset:50176
	ds_read_b64_tr_b16 v[86:87], v243 offset:50688
	global_load_lds_dwordx4 v223, s[4:5]
	v_mfma_f32_32x32x16_bf16 v[16:31], v[164:167], v[88:91], v[16:31]
	s_add_i32 m0, s21, 0xc000
	v_max3_f32 v246, v246, v134, v135
	v_max3_f32 v247, v247, v136, v137
	v_max3_f32 v246, v246, v138, v139
	v_max3_f32 v247, v247, v140, v141
	ds_read_b64_tr_b16 v[88:89], v243 offset:54272
	ds_read_b64_tr_b16 v[90:91], v243 offset:54784
	global_load_lds_dwordx4 v224, s[4:5]
	s_add_u32 s4, s4, 0x20000
	s_addc_u32 s5, s5, 0
	s_waitcnt lgkmcnt(8)
	v_mfma_f32_32x32x16_bf16 v[0:15], v[168:171], v[92:95], v[0:15]
	v_max3_f32 v246, v246, v142, v143
	v_max_f32_e32 v248, v246, v247
	v_mov_b32_e32 v246, v248
	ds_read_b64_tr_b16 v[92:93], v243 offset:51200
	ds_read_b64_tr_b16 v[94:95], v243 offset:51712
	v_permlane32_swap_b32_e32 v248, v246
	v_max_f32_e32 v248, v248, v246
	v_cmp_lt_f32_e32 vcc, s87, v248
	s_cbranch_vccnz .Lat_rare_T5

; __device__ __forceinline__ void cmask(f32x16&p0,f32x16&p1,int jb,int qrel,int hi){
;   const float NEG=-INFINITY; int kb=64*jb+4*hi;
;   #pragma unroll
;   for(int r=0;r<16;++r){int kv=kb+(r&3)+8*(r>>2); if(kv>qrel)p0[r]=NEG; if(kv+32>qrel)p1[r]=NEG;}
; }
.Lat_step_T4:
	v_add_u32_e32 v243, s16, v204
	ds_read_b64_tr_b16 v[214:215], v243 offset:24576
	ds_read_b64_tr_b16 v[216:217], v243 offset:25088
	v_mfma_f32_32x32x16_bf16 v[80:95], v[176:179], v[144:147], v[64:79]
	v_add_f32_e32 v245, v112, v113
	v_add_f32_e32 v245, v114, v245
	v_add_f32_e32 v245, v115, v245
	v_add_f32_e32 v245, v116, v245
	v_add_f32_e32 v245, v117, v245
	v_cvt_pk_bf16_f32 v160, v112, v113
	v_cvt_pk_bf16_f32 v161, v114, v115
	ds_read_b64_tr_b16 v[112:113], v243 offset:28672
	ds_read_b64_tr_b16 v[114:115], v243 offset:29184
	v_mfma_f32_32x32x16_bf16 v[96:111], v[180:183], v[144:147], v[64:79]
	v_add_f32_e32 v245, v118, v245
	v_add_f32_e32 v245, v119, v245
	v_add_f32_e32 v245, v120, v245
	v_add_f32_e32 v245, v121, v245
	v_cvt_pk_bf16_f32 v162, v116, v117
	v_cvt_pk_bf16_f32 v163, v118, v119
	ds_read_b64_tr_b16 v[116:117], v243 offset:25600
	ds_read_b64_tr_b16 v[118:119], v243 offset:26112
	v_mfma_f32_32x32x16_bf16 v[80:95], v[184:187], v[148:151], v[80:95]
	v_add_f32_e32 v245, v122, v245
	v_add_f32_e32 v245, v123, v245
	v_add_f32_e32 v245, v124, v245
	v_add_f32_e32 v245, v125, v245
	v_cvt_pk_bf16_f32 v164, v120, v121
	v_cvt_pk_bf16_f32 v165, v122, v123
	ds_read_b64_tr_b16 v[120:121], v243 offset:29696
	ds_read_b64_tr_b16 v[122:123], v243 offset:30208
	v_mfma_f32_32x32x16_bf16 v[96:111], v[188:191], v[148:151], v[96:111]
	v_add_f32_e32 v245, v126, v245
	v_add_f32_e32 v245, v127, v245
	v_add_f32_e32 v245, v128, v245
	v_add_f32_e32 v245, v129, v245
	v_cvt_pk_bf16_f32 v166, v124, v125
	v_cvt_pk_bf16_f32 v167, v126, v127
	ds_read_b64_tr_b16 v[124:125], v243 offset:26624
	ds_read_b64_tr_b16 v[126:127], v243 offset:27136
	v_mfma_f32_32x32x16_bf16 v[80:95], v[192:195], v[152:155], v[80:95]
	v_add_f32_e32 v245, v130, v245
	v_add_f32_e32 v245, v131, v245
	v_add_f32_e32 v245, v132, v245
	v_add_f32_e32 v245, v133, v245
	v_cvt_pk_bf16_f32 v168, v128, v129
	v_cvt_pk_bf16_f32 v169, v130, v131
	ds_read_b64_tr_b16 v[128:129], v243 offset:30720
	ds_read_b64_tr_b16 v[130:131], v243 offset:31232
	v_mfma_f32_32x32x16_bf16 v[96:111], v[196:199], v[152:155], v[96:111]
	v_add_f32_e32 v245, v134, v245
	v_add_f32_e32 v245, v135, v245
	v_add_f32_e32 v245, v136, v245
	v_add_f32_e32 v245, v137, v245
	v_cvt_pk_bf16_f32 v170, v132, v133
	v_cvt_pk_bf16_f32 v171, v134, v135
	ds_read_b64_tr_b16 v[132:133], v243 offset:27648
	ds_read_b64_tr_b16 v[134:135], v243 offset:28160
	v_mfma_f32_32x32x16_bf16 v[80:95], v[200:203], v[156:159], v[80:95]
	v_add_f32_e32 v245, v138, v245
	v_add_f32_e32 v245, v139, v245
	v_add_f32_e32 v245, v140, v245
	v_add_f32_e32 v245, v141, v245
	v_cvt_pk_bf16_f32 v172, v136, v137
	v_cvt_pk_bf16_f32 v173, v138, v139
	ds_read_b64_tr_b16 v[136:137], v243 offset:31744
	ds_read_b64_tr_b16 v[138:139], v243 offset:32256
	v_mfma_f32_32x32x16_bf16 v[96:111], v[206:209], v[156:159], v[96:111]
	v_add_f32_e32 v245, v142, v245
	v_add_f32_e32 v245, v143, v245
	v_cvt_pk_bf16_f32 v174, v140, v141
	v_cvt_pk_bf16_f32 v175, v142, v143
	v_add_f32_e32 v211, v211, v245
	v_add_u32_e32 v244, s18, v219
	s_waitcnt lgkmcnt(8)
	v_mfma_f32_32x32x16_bf16 v[0:15], v[160:163], v[214:217], v[0:15]
	v_cmp_gt_i32_e64 s[28:29], 0, v225
	v_cmp_gt_i32_e64 s[30:31], 1, v225
	v_cmp_gt_i32_e64 s[34:35], 2, v225
	v_cndmask_b32_e64 v80, v80, v241, s[28:29]
	v_cmp_gt_i32_e64 s[28:29], 3, v225
	v_cndmask_b32_e64 v81, v81, v241, s[30:31]
	v_cmp_gt_i32_e64 s[30:31], 8, v225
	v_cndmask_b32_e64 v82, v82, v241, s[34:35]
	v_cmp_gt_i32_e64 s[34:35], 9, v225
	v_cndmask_b32_e64 v83, v83, v241, s[28:29]
	ds_read_b64_tr_b16 v[214:215], v243 offset:49152
	ds_read_b64_tr_b16 v[216:217], v243 offset:49664
	v_mfma_f32_32x32x16_bf16 v[16:31], v[160:163], v[112:115], v[16:31]
	s_add_i32 m0, s17, s54
	v_cmp_gt_i32_e64 s[28:29], 10, v225
	v_cndmask_b32_e64 v84, v84, v241, s[30:31]
	v_cmp_gt_i32_e64 s[30:31], 11, v225
	v_cndmask_b32_e64 v85, v85, v241, s[34:35]
	v_cmp_gt_i32_e64 s[34:35], 16, v225
	v_cndmask_b32_e64 v86, v86, v241, s[28:29]
	v_cmp_gt_i32_e64 s[28:29], 17, v225
	v_cndmask_b32_e64 v87, v87, v241, s[30:31]
	v_cmp_gt_i32_e64 s[30:31], 18, v225
	v_cndmask_b32_e64 v88, v88, v241, s[34:35]
	ds_read_b64_tr_b16 v[112:113], v243 offset:53248
	ds_read_b64_tr_b16 v[114:115], v243 offset:53760
	global_load_lds_dwordx4 v222, s[0:1]
	s_add_u32 s0, s0, 0x20000
	s_addc_u32 s1, s1, 0
	v_mfma_f32_32x32x16_bf16 v[0:15], v[164:167], v[116:119], v[0:15]
	s_add_i32 s21, s18, s54
	s_add_i32 m0, s21, 0x6000
	v_cmp_gt_i32_e64 s[34:35], 19, v225
	v_cndmask_b32_e64 v89, v89, v241, s[28:29]
	v_cmp_gt_i32_e64 s[28:29], 24, v225
	v_cndmask_b32_e64 v90, v90, v241, s[30:31]
	v_cmp_gt_i32_e64 s[30:31], 25, v225
	v_cndmask_b32_e64 v91, v91, v241, s[34:35]
	v_cmp_gt_i32_e64 s[34:35], 26, v225
	v_cndmask_b32_e64 v92, v92, v241, s[28:29]
	v_cmp_gt_i32_e64 s[28:29], 27, v225
	v_cndmask_b32_e64 v93, v93, v241, s[30:31]
	ds_read_b64_tr_b16 v[116:117], v243 offset:50176
	ds_read_b64_tr_b16 v[118:119], v243 offset:50688
	global_load_lds_dwordx4 v223, s[4:5]
	v_mfma_f32_32x32x16_bf16 v[16:31], v[164:167], v[120:123], v[16:31]
	s_add_i32 m0, s21, 0xc000
	v_cmp_gt_i32_e64 s[30:31], 32, v225
	v_cndmask_b32_e64 v94, v94, v241, s[34:35]
	v_cmp_gt_i32_e64 s[34:35], 33, v225
	v_cndmask_b32_e64 v95, v95, v241, s[28:29]
	v_cmp_gt_i32_e64 s[28:29], 34, v225
	v_cndmask_b32_e64 v96, v96, v241, s[30:31]
	v_cmp_gt_i32_e64 s[30:31], 35, v225
	v_cndmask_b32_e64 v97, v97, v241, s[34:35]
	v_cmp_gt_i32_e64 s[34:35], 40, v225
	v_cndmask_b32_e64 v98, v98, v241, s[28:29]
	ds_read_b64_tr_b16 v[120:121], v243 offset:54272
	ds_read_b64_tr_b16 v[122:123], v243 offset:54784
	global_load_lds_dwordx4 v224, s[4:5]
	s_add_u32 s4, s4, 0x20000
	s_addc_u32 s5, s5, 0
	s_waitcnt lgkmcnt(8)
; __device__ __forceinline__ void cmask(f32x16&p0,f32x16&p1,int jb,int qrel,int hi){
;   const float NEG=-INFINITY; int kb=64*jb+4*hi;
;   #pragma unroll
;   for(int r=0;r<16;++r){int kv=kb+(r&3)+8*(r>>2); if(kv>qrel)p0[r]=NEG; if(kv+32>qrel)p1[r]=NEG;}
; }
	v_mfma_f32_32x32x16_bf16 v[0:15], v[168:171], v[124:127], v[0:15]
	v_cmp_gt_i32_e64 s[28:29], 41, v225
	v_cndmask_b32_e64 v99, v99, v241, s[30:31]
	v_cmp_gt_i32_e64 s[30:31], 42, v225
	v_cndmask_b32_e64 v100, v100, v241, s[34:35]
	v_cmp_gt_i32_e64 s[34:35], 43, v225
	v_cndmask_b32_e64 v101, v101, v241, s[28:29]
	v_cmp_gt_i32_e64 s[28:29], 48, v225
	v_cndmask_b32_e64 v102, v102, v241, s[30:31]
	v_cmp_gt_i32_e64 s[30:31], 49, v225
	v_cndmask_b32_e64 v103, v103, v241, s[34:35]
	ds_read_b64_tr_b16 v[124:125], v243 offset:51200
	ds_read_b64_tr_b16 v[126:127], v243 offset:51712
	v_mfma_f32_32x32x16_bf16 v[16:31], v[168:171], v[128:131], v[16:31]
	v_cmp_gt_i32_e64 s[34:35], 50, v225
	v_cndmask_b32_e64 v104, v104, v241, s[28:29]
	v_cmp_gt_i32_e64 s[28:29], 51, v225
	v_cndmask_b32_e64 v105, v105, v241, s[30:31]
	v_cmp_gt_i32_e64 s[30:31], 56, v225
	v_cndmask_b32_e64 v106, v106, v241, s[34:35]
	v_cmp_gt_i32_e64 s[34:35], 57, v225
	v_cndmask_b32_e64 v107, v107, v241, s[28:29]
	v_cmp_gt_i32_e64 s[28:29], 58, v225
	v_cndmask_b32_e64 v108, v108, v241, s[30:31]
	ds_read_b64_tr_b16 v[128:129], v243 offset:55296
	ds_read_b64_tr_b16 v[130:131], v243 offset:55808
	v_mfma_f32_32x32x16_bf16 v[0:15], v[172:175], v[132:135], v[0:15]
	v_cmp_gt_i32_e64 s[30:31], 59, v225
	v_cndmask_b32_e64 v109, v109, v241, s[34:35]
	v_cndmask_b32_e64 v110, v110, v241, s[28:29]
	v_cndmask_b32_e64 v111, v111, v241, s[30:31]
	v_max3_f32 v246, v80, v81, v82
	v_max3_f32 v247, v83, v84, v85
	v_max3_f32 v246, v246, v86, v87
	v_max3_f32 v247, v247, v88, v89
	v_max3_f32 v246, v246, v90, v91
	v_max3_f32 v247, v247, v92, v93
	ds_read_b64_tr_b16 v[132:133], v243 offset:52224
	ds_read_b64_tr_b16 v[134:135], v243 offset:52736
	v_mfma_f32_32x32x16_bf16 v[16:31], v[172:175], v[136:139], v[16:31]
	v_max3_f32 v246, v246, v94, v95
	v_max3_f32 v247, v247, v96, v97
	v_max3_f32 v246, v246, v98, v99
	v_max3_f32 v247, v247, v100, v101
	v_max3_f32 v246, v246, v102, v103
	v_max3_f32 v247, v247, v104, v105
	v_max3_f32 v246, v246, v106, v107
	v_max3_f32 v247, v247, v108, v109
	v_max3_f32 v246, v246, v110, v111
	v_max_f32_e32 v248, v246, v247
	ds_read_b64_tr_b16 v[136:137], v243 offset:56320
	ds_read_b64_tr_b16 v[138:139], v243 offset:56832
	s_waitcnt lgkmcnt(8)
	v_mfma_f32_32x32x16_bf16 v[32:47], v[160:163], v[214:217], v[32:47]
	v_mov_b32_e32 v246, v248
	s_nop 1
	v_permlane32_swap_b32_e32 v248, v246
	v_max_f32_e32 v248, v248, v246
	ds_read_b128 v[176:179], v244 offset:0
	ds_read_b128 v[180:183], v244 offset:512
	v_cmp_lt_f32_e32 vcc, s87, v248
	s_cbranch_vccnz .Lat_rare_T4
.Lat_cont_T4:
	v_mfma_f32_32x32x16_bf16 v[48:63], v[160:163], v[112:115], v[48:63]
	v_exp_f32_e32 v80, v80
	v_exp_f32_e32 v81, v81
	v_exp_f32_e32 v82, v82
	v_exp_f32_e32 v83, v83
	v_exp_f32_e32 v84, v84
	ds_read_b128 v[184:187], v244 offset:2048
	ds_read_b128 v[188:191], v244 offset:2560
	v_mfma_f32_32x32x16_bf16 v[32:47], v[164:167], v[116:119], v[32:47]
	v_exp_f32_e32 v85, v85
	v_exp_f32_e32 v86, v86
	v_exp_f32_e32 v87, v87
	v_exp_f32_e32 v88, v88
	v_exp_f32_e32 v89, v89
	ds_read_b128 v[192:195], v244 offset:4096
	ds_read_b128 v[196:199], v244 offset:4608
	v_mfma_f32_32x32x16_bf16 v[48:63], v[164:167], v[120:123], v[48:63]
	v_exp_f32_e32 v90, v90
	v_exp_f32_e32 v91, v91
	v_exp_f32_e32 v92, v92
	v_exp_f32_e32 v93, v93
	v_exp_f32_e32 v94, v94
	ds_read_b128 v[200:203], v244 offset:6144
	ds_read_b128 v[206:209], v244 offset:6656
	s_waitcnt lgkmcnt(8)
	v_mfma_f32_32x32x16_bf16 v[32:47], v[168:171], v[124:127], v[32:47]
	v_exp_f32_e32 v95, v95
	v_exp_f32_e32 v96, v96
	v_exp_f32_e32 v97, v97
	v_exp_f32_e32 v98, v98
	v_exp_f32_e32 v99, v99
	v_mfma_f32_32x32x16_bf16 v[48:63], v[168:171], v[128:131], v[48:63]
	v_exp_f32_e32 v100, v100
	v_exp_f32_e32 v101, v101
	v_exp_f32_e32 v102, v102
	v_exp_f32_e32 v103, v103
	v_mfma_f32_32x32x16_bf16 v[32:47], v[172:175], v[132:135], v[32:47]
	v_exp_f32_e32 v104, v104
	v_exp_f32_e32 v105, v105
	v_exp_f32_e32 v106, v106
	v_exp_f32_e32 v107, v107
	v_mfma_f32_32x32x16_bf16 v[48:63], v[172:175], v[136:139], v[48:63]
	v_exp_f32_e32 v108, v108
	v_exp_f32_e32 v109, v109
	v_exp_f32_e32 v110, v110
	v_exp_f32_e32 v111, v111
	s_waitcnt vmcnt(3) lgkmcnt(0)
	s_barrier
	s_cbranch_vccz .Lat_noresc_T4
	s_waitcnt lgkmcnt(0)
	ds_read_b128 v[214:217], v227 offset:0
	s_waitcnt lgkmcnt(0)
	v_pk_mul_f32 v[0:1], v[0:1], v[214:215]
	v_pk_mul_f32 v[2:3], v[2:3], v[216:217]
	v_pk_mul_f32 v[16:17], v[16:17], v[214:215]
	v_pk_mul_f32 v[18:19], v[18:19], v[216:217]
	v_pk_mul_f32 v[32:33], v[32:33], v[214:215]
	v_pk_mul_f32 v[34:35], v[34:35], v[216:217]
	v_pk_mul_f32 v[48:49], v[48:49], v[214:215]
	v_pk_mul_f32 v[50:51], v[50:51], v[216:217]
	ds_read_b128 v[214:217], v227 offset:32
	s_waitcnt lgkmcnt(0)
	v_pk_mul_f32 v[4:5], v[4:5], v[214:215]
	v_pk_mul_f32 v[6:7], v[6:7], v[216:217]
	v_pk_mul_f32 v[20:21], v[20:21], v[214:215]
	v_pk_mul_f32 v[22:23], v[22:23], v[216:217]
	v_pk_mul_f32 v[36:37], v[36:37], v[214:215]
	v_pk_mul_f32 v[38:39], v[38:39], v[216:217]
	v_pk_mul_f32 v[52:53], v[52:53], v[214:215]
	v_pk_mul_f32 v[54:55], v[54:55], v[216:217]
	ds_read_b128 v[214:217], v227 offset:64
	s_waitcnt lgkmcnt(0)
	v_pk_mul_f32 v[8:9], v[8:9], v[214:215]
	v_pk_mul_f32 v[10:11], v[10:11], v[216:217]
	v_pk_mul_f32 v[24:25], v[24:25], v[214:215]
	v_pk_mul_f32 v[26:27], v[26:27], v[216:217]
	v_pk_mul_f32 v[40:41], v[40:41], v[214:215]
	v_pk_mul_f32 v[42:43], v[42:43], v[216:217]
	v_pk_mul_f32 v[56:57], v[56:57], v[214:215]
	v_pk_mul_f32 v[58:59], v[58:59], v[216:217]
	ds_read_b128 v[214:217], v227 offset:96
	s_waitcnt lgkmcnt(0)
	v_pk_mul_f32 v[12:13], v[12:13], v[214:215]
	v_pk_mul_f32 v[14:15], v[14:15], v[216:217]
	v_pk_mul_f32 v[28:29], v[28:29], v[214:215]
	v_pk_mul_f32 v[30:31], v[30:31], v[216:217]
	v_pk_mul_f32 v[44:45], v[44:45], v[214:215]
	v_pk_mul_f32 v[46:47], v[46:47], v[216:217]
	v_pk_mul_f32 v[60:61], v[60:61], v[214:215]
	v_pk_mul_f32 v[62:63], v[62:63], v[216:217]

; __device__ __forceinline__ void cmask(f32x16&p0,f32x16&p1,int jb,int qrel,int hi){
;   const float NEG=-INFINITY; int kb=64*jb+4*hi;
;   #pragma unroll
;   for(int r=0;r<16;++r){int kv=kb+(r&3)+8*(r>>2); if(kv>qrel)p0[r]=NEG; if(kv+32>qrel)p1[r]=NEG;}
; }
.Lat_step_T3:
	v_add_u32_e32 v243, s16, v204
	ds_read_b64_tr_b16 v[214:215], v243 offset:24576
	ds_read_b64_tr_b16 v[216:217], v243 offset:25088
	v_mfma_f32_32x32x16_bf16 v[112:127], v[176:179], v[144:147], v[64:79]
	v_add_f32_e32 v245, v80, v81
	v_add_f32_e32 v245, v82, v245
	v_add_f32_e32 v245, v83, v245
	v_add_f32_e32 v245, v84, v245
	v_add_f32_e32 v245, v85, v245
	v_cvt_pk_bf16_f32 v160, v80, v81
	v_cvt_pk_bf16_f32 v161, v82, v83
	ds_read_b64_tr_b16 v[80:81], v243 offset:28672
	ds_read_b64_tr_b16 v[82:83], v243 offset:29184
	v_mfma_f32_32x32x16_bf16 v[128:143], v[180:183], v[144:147], v[64:79]
	v_add_f32_e32 v245, v86, v245
	v_add_f32_e32 v245, v87, v245
	v_add_f32_e32 v245, v88, v245
	v_add_f32_e32 v245, v89, v245
	v_cvt_pk_bf16_f32 v162, v84, v85
	v_cvt_pk_bf16_f32 v163, v86, v87
	ds_read_b64_tr_b16 v[84:85], v243 offset:25600
	ds_read_b64_tr_b16 v[86:87], v243 offset:26112
	v_mfma_f32_32x32x16_bf16 v[112:127], v[184:187], v[148:151], v[112:127]
	v_add_f32_e32 v245, v90, v245
	v_add_f32_e32 v245, v91, v245
	v_add_f32_e32 v245, v92, v245
	v_add_f32_e32 v245, v93, v245
	v_cvt_pk_bf16_f32 v164, v88, v89
	v_cvt_pk_bf16_f32 v165, v90, v91
	ds_read_b64_tr_b16 v[88:89], v243 offset:29696
	ds_read_b64_tr_b16 v[90:91], v243 offset:30208
	v_mfma_f32_32x32x16_bf16 v[128:143], v[188:191], v[148:151], v[128:143]
	v_add_f32_e32 v245, v94, v245
	v_add_f32_e32 v245, v95, v245
	v_add_f32_e32 v245, v96, v245
	v_add_f32_e32 v245, v97, v245
	v_cvt_pk_bf16_f32 v166, v92, v93
	v_cvt_pk_bf16_f32 v167, v94, v95
	ds_read_b64_tr_b16 v[92:93], v243 offset:26624
	ds_read_b64_tr_b16 v[94:95], v243 offset:27136
	v_mfma_f32_32x32x16_bf16 v[112:127], v[192:195], v[152:155], v[112:127]
	v_add_f32_e32 v245, v98, v245
	v_add_f32_e32 v245, v99, v245
	v_add_f32_e32 v245, v100, v245
	v_add_f32_e32 v245, v101, v245
	v_cvt_pk_bf16_f32 v168, v96, v97
	v_cvt_pk_bf16_f32 v169, v98, v99
	ds_read_b64_tr_b16 v[96:97], v243 offset:30720
	ds_read_b64_tr_b16 v[98:99], v243 offset:31232
	v_mfma_f32_32x32x16_bf16 v[128:143], v[196:199], v[152:155], v[128:143]
	v_add_f32_e32 v245, v102, v245
	v_add_f32_e32 v245, v103, v245
	v_add_f32_e32 v245, v104, v245
	v_add_f32_e32 v245, v105, v245
	v_cvt_pk_bf16_f32 v170, v100, v101
	v_cvt_pk_bf16_f32 v171, v102, v103
	ds_read_b64_tr_b16 v[100:101], v243 offset:27648
	ds_read_b64_tr_b16 v[102:103], v243 offset:28160
	v_mfma_f32_32x32x16_bf16 v[112:127], v[200:203], v[156:159], v[112:127]
	v_add_f32_e32 v245, v106, v245
	v_add_f32_e32 v245, v107, v245
	v_add_f32_e32 v245, v108, v245
	v_add_f32_e32 v245, v109, v245
	v_cvt_pk_bf16_f32 v172, v104, v105
	v_cvt_pk_bf16_f32 v173, v106, v107
	ds_read_b64_tr_b16 v[104:105], v243 offset:31744
	ds_read_b64_tr_b16 v[106:107], v243 offset:32256
	v_mfma_f32_32x32x16_bf16 v[128:143], v[206:209], v[156:159], v[128:143]
	v_add_f32_e32 v245, v110, v245
	v_add_f32_e32 v245, v111, v245
	v_cvt_pk_bf16_f32 v174, v108, v109
	v_cvt_pk_bf16_f32 v175, v110, v111
	v_add_f32_e32 v211, v211, v245
	v_add_u32_e32 v244, s18, v219
	s_waitcnt lgkmcnt(8)
	v_mfma_f32_32x32x16_bf16 v[0:15], v[160:163], v[214:217], v[0:15]
	v_add_u32_e32 v242, 0xffffffc0, v225
	v_cmp_gt_i32_e64 s[28:29], 0, v242
	v_cmp_gt_i32_e64 s[30:31], 1, v242
	v_cmp_gt_i32_e64 s[34:35], 2, v242
	v_cndmask_b32_e64 v112, v112, v241, s[28:29]
	v_cmp_gt_i32_e64 s[28:29], 3, v242
	v_cndmask_b32_e64 v113, v113, v241, s[30:31]
	v_cmp_gt_i32_e64 s[30:31], 8, v242
	v_cndmask_b32_e64 v114, v114, v241, s[34:35]
	v_cmp_gt_i32_e64 s[34:35], 9, v242
	ds_read_b64_tr_b16 v[214:215], v243 offset:49152
	ds_read_b64_tr_b16 v[216:217], v243 offset:49664
	v_mfma_f32_32x32x16_bf16 v[16:31], v[160:163], v[80:83], v[16:31]
	v_cndmask_b32_e64 v115, v115, v241, s[28:29]
	v_cmp_gt_i32_e64 s[28:29], 10, v242
	v_cndmask_b32_e64 v116, v116, v241, s[30:31]
	v_cmp_gt_i32_e64 s[30:31], 11, v242
	v_cndmask_b32_e64 v117, v117, v241, s[34:35]
	v_cmp_gt_i32_e64 s[34:35], 16, v242
	v_cndmask_b32_e64 v118, v118, v241, s[28:29]
	v_cmp_gt_i32_e64 s[28:29], 17, v242
	v_cndmask_b32_e64 v119, v119, v241, s[30:31]
	v_cmp_gt_i32_e64 s[30:31], 18, v242
	ds_read_b64_tr_b16 v[80:81], v243 offset:53248
	ds_read_b64_tr_b16 v[82:83], v243 offset:53760
	v_mfma_f32_32x32x16_bf16 v[0:15], v[164:167], v[84:87], v[0:15]
	s_add_i32 s21, s18, s54
	s_add_i32 m0, s21, 0x6000
	v_cndmask_b32_e64 v120, v120, v241, s[34:35]
	v_cmp_gt_i32_e64 s[34:35], 19, v242
	v_cndmask_b32_e64 v121, v121, v241, s[28:29]
	v_cmp_gt_i32_e64 s[28:29], 24, v242
	v_cndmask_b32_e64 v122, v122, v241, s[30:31]
	v_cmp_gt_i32_e64 s[30:31], 25, v242
	v_cndmask_b32_e64 v123, v123, v241, s[34:35]
	v_cmp_gt_i32_e64 s[34:35], 26, v242
	v_cndmask_b32_e64 v124, v124, v241, s[28:29]
	v_cmp_gt_i32_e64 s[28:29], 27, v242
	ds_read_b64_tr_b16 v[84:85], v243 offset:50176
	ds_read_b64_tr_b16 v[86:87], v243 offset:50688
	global_load_lds_dwordx4 v223, s[4:5]
	v_mfma_f32_32x32x16_bf16 v[16:31], v[164:167], v[88:91], v[16:31]
	s_add_i32 m0, s21, 0xc000
	v_cndmask_b32_e64 v125, v125, v241, s[30:31]
	v_cmp_gt_i32_e64 s[30:31], 32, v242
	v_cndmask_b32_e64 v126, v126, v241, s[34:35]
	v_cmp_gt_i32_e64 s[34:35], 33, v242
	v_cndmask_b32_e64 v127, v127, v241, s[28:29]
	v_cmp_gt_i32_e64 s[28:29], 34, v242
	v_cndmask_b32_e64 v128, v128, v241, s[30:31]
	v_cmp_gt_i32_e64 s[30:31], 35, v242
	v_cndmask_b32_e64 v129, v129, v241, s[34:35]
	v_cmp_gt_i32_e64 s[34:35], 40, v242
	ds_read_b64_tr_b16 v[88:89], v243 offset:54272
	ds_read_b64_tr_b16 v[90:91], v243 offset:54784
	global_load_lds_dwordx4 v224, s[4:5]
	s_add_u32 s4, s4, 0x20000
	s_addc_u32 s5, s5, 0
	s_waitcnt lgkmcnt(8)
; __device__ __forceinline__ void cmask(f32x16&p0,f32x16&p1,int jb,int qrel,int hi){
;   const float NEG=-INFINITY; int kb=64*jb+4*hi;
;   #pragma unroll
;   for(int r=0;r<16;++r){int kv=kb+(r&3)+8*(r>>2); if(kv>qrel)p0[r]=NEG; if(kv+32>qrel)p1[r]=NEG;}
; }
	v_mfma_f32_32x32x16_bf16 v[0:15], v[168:171], v[92:95], v[0:15]
	v_cndmask_b32_e64 v130, v130, v241, s[28:29]
	v_cmp_gt_i32_e64 s[28:29], 41, v242
	v_cndmask_b32_e64 v131, v131, v241, s[30:31]
	v_cmp_gt_i32_e64 s[30:31], 42, v242
	v_cndmask_b32_e64 v132, v132, v241, s[34:35]
	v_cmp_gt_i32_e64 s[34:35], 43, v242
	v_cndmask_b32_e64 v133, v133, v241, s[28:29]
	v_cmp_gt_i32_e64 s[28:29], 48, v242
	v_cndmask_b32_e64 v134, v134, v241, s[30:31]
	v_cmp_gt_i32_e64 s[30:31], 49, v242
	ds_read_b64_tr_b16 v[92:93], v243 offset:51200
	ds_read_b64_tr_b16 v[94:95], v243 offset:51712
	v_mfma_f32_32x32x16_bf16 v[16:31], v[168:171], v[96:99], v[16:31]
	v_cndmask_b32_e64 v135, v135, v241, s[34:35]
	v_cmp_gt_i32_e64 s[34:35], 50, v242
	v_cndmask_b32_e64 v136, v136, v241, s[28:29]
	v_cmp_gt_i32_e64 s[28:29], 51, v242
	v_cndmask_b32_e64 v137, v137, v241, s[30:31]
	v_cmp_gt_i32_e64 s[30:31], 56, v242
	v_cndmask_b32_e64 v138, v138, v241, s[34:35]
	v_cmp_gt_i32_e64 s[34:35], 57, v242
	v_cndmask_b32_e64 v139, v139, v241, s[28:29]
	v_cmp_gt_i32_e64 s[28:29], 58, v242
	ds_read_b64_tr_b16 v[96:97], v243 offset:55296
	ds_read_b64_tr_b16 v[98:99], v243 offset:55808
	v_mfma_f32_32x32x16_bf16 v[0:15], v[172:175], v[100:103], v[0:15]
	v_cndmask_b32_e64 v140, v140, v241, s[30:31]
	v_cmp_gt_i32_e64 s[30:31], 59, v242
	v_cndmask_b32_e64 v141, v141, v241, s[34:35]
	v_cndmask_b32_e64 v142, v142, v241, s[28:29]
	v_cndmask_b32_e64 v143, v143, v241, s[30:31]
	v_max3_f32 v246, v112, v113, v114
	v_max3_f32 v247, v115, v116, v117
	v_max3_f32 v246, v246, v118, v119
	v_max3_f32 v247, v247, v120, v121
	v_max3_f32 v246, v246, v122, v123
	ds_read_b64_tr_b16 v[100:101], v243 offset:52224
	ds_read_b64_tr_b16 v[102:103], v243 offset:52736
	v_mfma_f32_32x32x16_bf16 v[16:31], v[172:175], v[104:107], v[16:31]
	v_max3_f32 v247, v247, v124, v125
	v_max3_f32 v246, v246, v126, v127
	v_max3_f32 v247, v247, v128, v129
	v_max3_f32 v246, v246, v130, v131
	v_max3_f32 v247, v247, v132, v133
	v_max3_f32 v246, v246, v134, v135
	v_max3_f32 v247, v247, v136, v137
	v_max3_f32 v246, v246, v138, v139
	v_max3_f32 v247, v247, v140, v141
	v_max3_f32 v246, v246, v142, v143
	ds_read_b64_tr_b16 v[104:105], v243 offset:56320
	ds_read_b64_tr_b16 v[106:107], v243 offset:56832
	s_waitcnt lgkmcnt(8)
	v_mfma_f32_32x32x16_bf16 v[32:47], v[160:163], v[214:217], v[32:47]
	v_max_f32_e32 v248, v246, v247
	v_mov_b32_e32 v246, v248
	s_nop 1
	v_permlane32_swap_b32_e32 v248, v246
	v_max_f32_e32 v248, v248, v246
	ds_read_b128 v[176:179], v244 offset:0
	ds_read_b128 v[180:183], v244 offset:512
	v_cmp_lt_f32_e32 vcc, s87, v248
	s_cbranch_vccnz .Lat_rare_T3
.Lat_cont_T3:
	v_mfma_f32_32x32x16_bf16 v[48:63], v[160:163], v[80:83], v[48:63]
	v_exp_f32_e32 v112, v112
	v_exp_f32_e32 v113, v113
	v_exp_f32_e32 v114, v114
	v_exp_f32_e32 v115, v115
	v_exp_f32_e32 v116, v116
	ds_read_b128 v[184:187], v244 offset:2048
	ds_read_b128 v[188:191], v244 offset:2560
	v_mfma_f32_32x32x16_bf16 v[32:47], v[164:167], v[84:87], v[32:47]
	v_exp_f32_e32 v117, v117
	v_exp_f32_e32 v118, v118
	v_exp_f32_e32 v119, v119
	v_exp_f32_e32 v120, v120
	v_exp_f32_e32 v121, v121
	ds_read_b128 v[192:195], v244 offset:4096
	ds_read_b128 v[196:199], v244 offset:4608
	v_mfma_f32_32x32x16_bf16 v[48:63], v[164:167], v[88:91], v[48:63]
	v_exp_f32_e32 v122, v122
	v_exp_f32_e32 v123, v123
	v_exp_f32_e32 v124, v124
	v_exp_f32_e32 v125, v125
	v_exp_f32_e32 v126, v126
	ds_read_b128 v[200:203], v244 offset:6144
	ds_read_b128 v[206:209], v244 offset:6656
	s_waitcnt lgkmcnt(8)
	v_mfma_f32_32x32x16_bf16 v[32:47], v[168:171], v[92:95], v[32:47]
	v_exp_f32_e32 v127, v127
	v_exp_f32_e32 v128, v128
	v_exp_f32_e32 v129, v129
	v_exp_f32_e32 v130, v130
	v_exp_f32_e32 v131, v131
	v_mfma_f32_32x32x16_bf16 v[48:63], v[168:171], v[96:99], v[48:63]
	v_exp_f32_e32 v132, v132
	v_exp_f32_e32 v133, v133
	v_exp_f32_e32 v134, v134
	v_exp_f32_e32 v135, v135
	v_mfma_f32_32x32x16_bf16 v[32:47], v[172:175], v[100:103], v[32:47]
	v_exp_f32_e32 v136, v136
	v_exp_f32_e32 v137, v137
	v_exp_f32_e32 v138, v138
	v_exp_f32_e32 v139, v139
	v_mfma_f32_32x32x16_bf16 v[48:63], v[172:175], v[104:107], v[48:63]
	v_exp_f32_e32 v140, v140
	v_exp_f32_e32 v141, v141
	v_exp_f32_e32 v142, v142
	v_exp_f32_e32 v143, v143
	s_waitcnt vmcnt(2) lgkmcnt(0)
	s_barrier
	s_cbranch_vccz .Lat_noresc_T3
	s_waitcnt lgkmcnt(0)
	ds_read_b128 v[214:217], v227 offset:0
	s_waitcnt lgkmcnt(0)
	v_pk_mul_f32 v[0:1], v[0:1], v[214:215]
	v_pk_mul_f32 v[2:3], v[2:3], v[216:217]
	v_pk_mul_f32 v[16:17], v[16:17], v[214:215]
	v_pk_mul_f32 v[18:19], v[18:19], v[216:217]
	v_pk_mul_f32 v[32:33], v[32:33], v[214:215]
	v_pk_mul_f32 v[34:35], v[34:35], v[216:217]
	v_pk_mul_f32 v[48:49], v[48:49], v[214:215]
	v_pk_mul_f32 v[50:51], v[50:51], v[216:217]
	ds_read_b128 v[214:217], v227 offset:32
	s_waitcnt lgkmcnt(0)
	v_pk_mul_f32 v[4:5], v[4:5], v[214:215]
	v_pk_mul_f32 v[6:7], v[6:7], v[216:217]
	v_pk_mul_f32 v[20:21], v[20:21], v[214:215]
	v_pk_mul_f32 v[22:23], v[22:23], v[216:217]
	v_pk_mul_f32 v[36:37], v[36:37], v[214:215]
	v_pk_mul_f32 v[38:39], v[38:39], v[216:217]
	v_pk_mul_f32 v[52:53], v[52:53], v[214:215]
	v_pk_mul_f32 v[54:55], v[54:55], v[216:217]
	ds_read_b128 v[214:217], v227 offset:64
	s_waitcnt lgkmcnt(0)
	v_pk_mul_f32 v[8:9], v[8:9], v[214:215]
	v_pk_mul_f32 v[10:11], v[10:11], v[216:217]
	v_pk_mul_f32 v[24:25], v[24:25], v[214:215]
	v_pk_mul_f32 v[26:27], v[26:27], v[216:217]
	v_pk_mul_f32 v[40:41], v[40:41], v[214:215]
	v_pk_mul_f32 v[42:43], v[42:43], v[216:217]
	v_pk_mul_f32 v[56:57], v[56:57], v[214:215]
	v_pk_mul_f32 v[58:59], v[58:59], v[216:217]
	ds_read_b128 v[214:217], v227 offset:96
	s_waitcnt lgkmcnt(0)
	v_pk_mul_f32 v[12:13], v[12:13], v[214:215]
	v_pk_mul_f32 v[14:15], v[14:15], v[216:217]
	v_pk_mul_f32 v[28:29], v[28:29], v[214:215]
	v_pk_mul_f32 v[30:31], v[30:31], v[216:217]
	v_pk_mul_f32 v[44:45], v[44:45], v[214:215]
	v_pk_mul_f32 v[46:47], v[46:47], v[216:217]
	v_pk_mul_f32 v[60:61], v[60:61], v[214:215]
	v_pk_mul_f32 v[62:63], v[62:63], v[216:217]

; __device__ __forceinline__ void cmask(f32x16&p0,f32x16&p1,int jb,int qrel,int hi){
;   const float NEG=-INFINITY; int kb=64*jb+4*hi;
;   #pragma unroll
;   for(int r=0;r<16;++r){int kv=kb+(r&3)+8*(r>>2); if(kv>qrel)p0[r]=NEG; if(kv+32>qrel)p1[r]=NEG;}
; }
.Lat_step_T2:
	v_add_u32_e32 v243, s16, v204
	ds_read_b64_tr_b16 v[214:215], v243 offset:24576
	ds_read_b64_tr_b16 v[216:217], v243 offset:25088
	v_mfma_f32_32x32x16_bf16 v[80:95], v[176:179], v[144:147], v[64:79]
	v_add_f32_e32 v245, v112, v113
	v_add_f32_e32 v245, v114, v245
	v_add_f32_e32 v245, v115, v245
	v_add_f32_e32 v245, v116, v245
	v_add_f32_e32 v245, v117, v245
	v_cvt_pk_bf16_f32 v160, v112, v113
	v_cvt_pk_bf16_f32 v161, v114, v115
	ds_read_b64_tr_b16 v[112:113], v243 offset:28672
	ds_read_b64_tr_b16 v[114:115], v243 offset:29184
	v_mfma_f32_32x32x16_bf16 v[96:111], v[180:183], v[144:147], v[64:79]
	v_add_f32_e32 v245, v118, v245
	v_add_f32_e32 v245, v119, v245
	v_add_f32_e32 v245, v120, v245
	v_add_f32_e32 v245, v121, v245
	v_cvt_pk_bf16_f32 v162, v116, v117
	v_cvt_pk_bf16_f32 v163, v118, v119
	ds_read_b64_tr_b16 v[116:117], v243 offset:25600
	ds_read_b64_tr_b16 v[118:119], v243 offset:26112
	v_mfma_f32_32x32x16_bf16 v[80:95], v[184:187], v[148:151], v[80:95]
	v_add_f32_e32 v245, v122, v245
	v_add_f32_e32 v245, v123, v245
	v_add_f32_e32 v245, v124, v245
	v_add_f32_e32 v245, v125, v245
	v_cvt_pk_bf16_f32 v164, v120, v121
	v_cvt_pk_bf16_f32 v165, v122, v123
	ds_read_b64_tr_b16 v[120:121], v243 offset:29696
	ds_read_b64_tr_b16 v[122:123], v243 offset:30208
	v_mfma_f32_32x32x16_bf16 v[96:111], v[188:191], v[148:151], v[96:111]
	v_add_f32_e32 v245, v126, v245
	v_add_f32_e32 v245, v127, v245
	v_add_f32_e32 v245, v128, v245
	v_add_f32_e32 v245, v129, v245
	v_cvt_pk_bf16_f32 v166, v124, v125
	v_cvt_pk_bf16_f32 v167, v126, v127
	ds_read_b64_tr_b16 v[124:125], v243 offset:26624
	ds_read_b64_tr_b16 v[126:127], v243 offset:27136
	v_mfma_f32_32x32x16_bf16 v[80:95], v[192:195], v[152:155], v[80:95]
	v_add_f32_e32 v245, v130, v245
	v_add_f32_e32 v245, v131, v245
	v_add_f32_e32 v245, v132, v245
	v_add_f32_e32 v245, v133, v245
	v_cvt_pk_bf16_f32 v168, v128, v129
	v_cvt_pk_bf16_f32 v169, v130, v131
	ds_read_b64_tr_b16 v[128:129], v243 offset:30720
	ds_read_b64_tr_b16 v[130:131], v243 offset:31232
	v_mfma_f32_32x32x16_bf16 v[96:111], v[196:199], v[152:155], v[96:111]
	v_add_f32_e32 v245, v134, v245
	v_add_f32_e32 v245, v135, v245
	v_add_f32_e32 v245, v136, v245
	v_add_f32_e32 v245, v137, v245
	v_cvt_pk_bf16_f32 v170, v132, v133
	v_cvt_pk_bf16_f32 v171, v134, v135
	ds_read_b64_tr_b16 v[132:133], v243 offset:27648
	ds_read_b64_tr_b16 v[134:135], v243 offset:28160
	v_mfma_f32_32x32x16_bf16 v[80:95], v[200:203], v[156:159], v[80:95]
	v_add_f32_e32 v245, v138, v245
	v_add_f32_e32 v245, v139, v245
	v_add_f32_e32 v245, v140, v245
	v_add_f32_e32 v245, v141, v245
	v_cvt_pk_bf16_f32 v172, v136, v137
	v_cvt_pk_bf16_f32 v173, v138, v139
	ds_read_b64_tr_b16 v[136:137], v243 offset:31744
	ds_read_b64_tr_b16 v[138:139], v243 offset:32256
	v_mfma_f32_32x32x16_bf16 v[96:111], v[206:209], v[156:159], v[96:111]
	v_add_f32_e32 v245, v142, v245
	v_add_f32_e32 v245, v143, v245
	v_cvt_pk_bf16_f32 v174, v140, v141
	v_cvt_pk_bf16_f32 v175, v142, v143
	v_add_f32_e32 v211, v211, v245
	v_add_u32_e32 v244, s18, v219
	s_waitcnt lgkmcnt(8)
	v_mfma_f32_32x32x16_bf16 v[0:15], v[160:163], v[214:217], v[0:15]
	v_add_u32_e32 v242, 0xffffff80, v225
	v_cmp_gt_i32_e64 s[28:29], 0, v242
	v_cmp_gt_i32_e64 s[30:31], 1, v242
	v_cmp_gt_i32_e64 s[34:35], 2, v242
	v_cndmask_b32_e64 v80, v80, v241, s[28:29]
	v_cmp_gt_i32_e64 s[28:29], 3, v242
	v_cndmask_b32_e64 v81, v81, v241, s[30:31]
	v_cmp_gt_i32_e64 s[30:31], 8, v242
	v_cndmask_b32_e64 v82, v82, v241, s[34:35]
	v_cmp_gt_i32_e64 s[34:35], 9, v242
	ds_read_b64_tr_b16 v[214:215], v243 offset:49152
	ds_read_b64_tr_b16 v[216:217], v243 offset:49664
	v_mfma_f32_32x32x16_bf16 v[16:31], v[160:163], v[112:115], v[16:31]
	v_cndmask_b32_e64 v83, v83, v241, s[28:29]
	v_cmp_gt_i32_e64 s[28:29], 10, v242
	v_cndmask_b32_e64 v84, v84, v241, s[30:31]
	v_cmp_gt_i32_e64 s[30:31], 11, v242
	v_cndmask_b32_e64 v85, v85, v241, s[34:35]
	v_cmp_gt_i32_e64 s[34:35], 16, v242
	v_cndmask_b32_e64 v86, v86, v241, s[28:29]
	v_cmp_gt_i32_e64 s[28:29], 17, v242
	v_cndmask_b32_e64 v87, v87, v241, s[30:31]
	v_cmp_gt_i32_e64 s[30:31], 18, v242
	ds_read_b64_tr_b16 v[112:113], v243 offset:53248
	ds_read_b64_tr_b16 v[114:115], v243 offset:53760
	v_mfma_f32_32x32x16_bf16 v[0:15], v[164:167], v[116:119], v[0:15]
	s_add_i32 s21, s18, s54
	s_add_i32 m0, s21, 0x6000
	v_cndmask_b32_e64 v88, v88, v241, s[34:35]
	v_cmp_gt_i32_e64 s[34:35], 19, v242
	v_cndmask_b32_e64 v89, v89, v241, s[28:29]
	v_cmp_gt_i32_e64 s[28:29], 24, v242
	v_cndmask_b32_e64 v90, v90, v241, s[30:31]
	v_cmp_gt_i32_e64 s[30:31], 25, v242
	v_cndmask_b32_e64 v91, v91, v241, s[34:35]
	v_cmp_gt_i32_e64 s[34:35], 26, v242
	v_cndmask_b32_e64 v92, v92, v241, s[28:29]
	v_cmp_gt_i32_e64 s[28:29], 27, v242
	ds_read_b64_tr_b16 v[116:117], v243 offset:50176
	ds_read_b64_tr_b16 v[118:119], v243 offset:50688
	global_load_lds_dwordx4 v223, s[4:5]
	v_mfma_f32_32x32x16_bf16 v[16:31], v[164:167], v[120:123], v[16:31]
	s_add_i32 m0, s21, 0xc000
	v_cndmask_b32_e64 v93, v93, v241, s[30:31]
	v_cmp_gt_i32_e64 s[30:31], 32, v242
	v_cndmask_b32_e64 v94, v94, v241, s[34:35]
	v_cmp_gt_i32_e64 s[34:35], 33, v242
	v_cndmask_b32_e64 v95, v95, v241, s[28:29]
	v_cmp_gt_i32_e64 s[28:29], 34, v242
	v_cndmask_b32_e64 v96, v96, v241, s[30:31]
	v_cmp_gt_i32_e64 s[30:31], 35, v242
	v_cndmask_b32_e64 v97, v97, v241, s[34:35]
	v_cmp_gt_i32_e64 s[34:35], 40, v242
	ds_read_b64_tr_b16 v[120:121], v243 offset:54272
	ds_read_b64_tr_b16 v[122:123], v243 offset:54784
	global_load_lds_dwordx4 v224, s[4:5]
	s_add_u32 s4, s4, 0x20000
	s_addc_u32 s5, s5, 0
	s_waitcnt lgkmcnt(8)
; __device__ __forceinline__ void cmask(f32x16&p0,f32x16&p1,int jb,int qrel,int hi){
;   const float NEG=-INFINITY; int kb=64*jb+4*hi;
;   #pragma unroll
;   for(int r=0;r<16;++r){int kv=kb+(r&3)+8*(r>>2); if(kv>qrel)p0[r]=NEG; if(kv+32>qrel)p1[r]=NEG;}
; }
	v_mfma_f32_32x32x16_bf16 v[0:15], v[168:171], v[124:127], v[0:15]
	v_cndmask_b32_e64 v98, v98, v241, s[28:29]
	v_cmp_gt_i32_e64 s[28:29], 41, v242
	v_cndmask_b32_e64 v99, v99, v241, s[30:31]
	v_cmp_gt_i32_e64 s[30:31], 42, v242
	v_cndmask_b32_e64 v100, v100, v241, s[34:35]
	v_cmp_gt_i32_e64 s[34:35], 43, v242
	v_cndmask_b32_e64 v101, v101, v241, s[28:29]
	v_cmp_gt_i32_e64 s[28:29], 48, v242
	v_cndmask_b32_e64 v102, v102, v241, s[30:31]
	v_cmp_gt_i32_e64 s[30:31], 49, v242
	ds_read_b64_tr_b16 v[124:125], v243 offset:51200
	ds_read_b64_tr_b16 v[126:127], v243 offset:51712
	v_mfma_f32_32x32x16_bf16 v[16:31], v[168:171], v[128:131], v[16:31]
	v_cndmask_b32_e64 v103, v103, v241, s[34:35]
	v_cmp_gt_i32_e64 s[34:35], 50, v242
	v_cndmask_b32_e64 v104, v104, v241, s[28:29]
	v_cmp_gt_i32_e64 s[28:29], 51, v242
	v_cndmask_b32_e64 v105, v105, v241, s[30:31]
	v_cmp_gt_i32_e64 s[30:31], 56, v242
	v_cndmask_b32_e64 v106, v106, v241, s[34:35]
	v_cmp_gt_i32_e64 s[34:35], 57, v242
	v_cndmask_b32_e64 v107, v107, v241, s[28:29]
	v_cmp_gt_i32_e64 s[28:29], 58, v242
	ds_read_b64_tr_b16 v[128:129], v243 offset:55296
	ds_read_b64_tr_b16 v[130:131], v243 offset:55808
	v_mfma_f32_32x32x16_bf16 v[0:15], v[172:175], v[132:135], v[0:15]
	v_cndmask_b32_e64 v108, v108, v241, s[30:31]
	v_cmp_gt_i32_e64 s[30:31], 59, v242
	v_cndmask_b32_e64 v109, v109, v241, s[34:35]
	v_cndmask_b32_e64 v110, v110, v241, s[28:29]
	v_cndmask_b32_e64 v111, v111, v241, s[30:31]
	v_max3_f32 v246, v80, v81, v82
	v_max3_f32 v247, v83, v84, v85
	v_max3_f32 v246, v246, v86, v87
	v_max3_f32 v247, v247, v88, v89
	v_max3_f32 v246, v246, v90, v91
	ds_read_b64_tr_b16 v[132:133], v243 offset:52224
	ds_read_b64_tr_b16 v[134:135], v243 offset:52736
	v_mfma_f32_32x32x16_bf16 v[16:31], v[172:175], v[136:139], v[16:31]
	v_max3_f32 v247, v247, v92, v93
	v_max3_f32 v246, v246, v94, v95
	v_max3_f32 v247, v247, v96, v97
	v_max3_f32 v246, v246, v98, v99
	v_max3_f32 v247, v247, v100, v101
	v_max3_f32 v246, v246, v102, v103
	v_max3_f32 v247, v247, v104, v105
	v_max3_f32 v246, v246, v106, v107
	v_max3_f32 v247, v247, v108, v109
	v_max3_f32 v246, v246, v110, v111
	ds_read_b64_tr_b16 v[136:137], v243 offset:56320
	ds_read_b64_tr_b16 v[138:139], v243 offset:56832
	s_waitcnt lgkmcnt(8)
	v_mfma_f32_32x32x16_bf16 v[32:47], v[160:163], v[214:217], v[32:47]
	v_max_f32_e32 v248, v246, v247
	v_mov_b32_e32 v246, v248
	s_nop 1
	v_permlane32_swap_b32_e32 v248, v246
	v_max_f32_e32 v248, v248, v246
	ds_read_b128 v[176:179], v244 offset:0
	ds_read_b128 v[180:183], v244 offset:512
	v_cmp_lt_f32_e32 vcc, s87, v248
	s_cbranch_vccnz .Lat_rare_T2
.Lat_cont_T2:
	v_mfma_f32_32x32x16_bf16 v[48:63], v[160:163], v[112:115], v[48:63]
	v_exp_f32_e32 v80, v80
	v_exp_f32_e32 v81, v81
	v_exp_f32_e32 v82, v82
	v_exp_f32_e32 v83, v83
	v_exp_f32_e32 v84, v84
	ds_read_b128 v[184:187], v244 offset:2048
	ds_read_b128 v[188:191], v244 offset:2560
	v_mfma_f32_32x32x16_bf16 v[32:47], v[164:167], v[116:119], v[32:47]
	v_exp_f32_e32 v85, v85
	v_exp_f32_e32 v86, v86
	v_exp_f32_e32 v87, v87
	v_exp_f32_e32 v88, v88
	v_exp_f32_e32 v89, v89
	ds_read_b128 v[192:195], v244 offset:4096
	ds_read_b128 v[196:199], v244 offset:4608
	v_mfma_f32_32x32x16_bf16 v[48:63], v[164:167], v[120:123], v[48:63]
	v_exp_f32_e32 v90, v90
	v_exp_f32_e32 v91, v91
	v_exp_f32_e32 v92, v92
	v_exp_f32_e32 v93, v93
	v_exp_f32_e32 v94, v94
	ds_read_b128 v[200:203], v244 offset:6144
	ds_read_b128 v[206:209], v244 offset:6656
	s_waitcnt lgkmcnt(8)
	v_mfma_f32_32x32x16_bf16 v[32:47], v[168:171], v[124:127], v[32:47]
	v_exp_f32_e32 v95, v95
	v_exp_f32_e32 v96, v96
	v_exp_f32_e32 v97, v97
	v_exp_f32_e32 v98, v98
	v_exp_f32_e32 v99, v99
	v_mfma_f32_32x32x16_bf16 v[48:63], v[168:171], v[128:131], v[48:63]
	v_exp_f32_e32 v100, v100
	v_exp_f32_e32 v101, v101
	v_exp_f32_e32 v102, v102
	v_exp_f32_e32 v103, v103
	v_mfma_f32_32x32x16_bf16 v[32:47], v[172:175], v[132:135], v[32:47]
	v_exp_f32_e32 v104, v104
	v_exp_f32_e32 v105, v105
	v_exp_f32_e32 v106, v106
	v_exp_f32_e32 v107, v107
	v_mfma_f32_32x32x16_bf16 v[48:63], v[172:175], v[136:139], v[48:63]
	v_exp_f32_e32 v108, v108
	v_exp_f32_e32 v109, v109
	v_exp_f32_e32 v110, v110
	v_exp_f32_e32 v111, v111
	s_waitcnt vmcnt(0) lgkmcnt(0)
	s_barrier
	s_cbranch_vccz .Lat_noresc_T2
	s_waitcnt lgkmcnt(0)
	ds_read_b128 v[214:217], v227 offset:0
	s_waitcnt lgkmcnt(0)
	v_pk_mul_f32 v[0:1], v[0:1], v[214:215]
	v_pk_mul_f32 v[2:3], v[2:3], v[216:217]
	v_pk_mul_f32 v[16:17], v[16:17], v[214:215]
	v_pk_mul_f32 v[18:19], v[18:19], v[216:217]
	v_pk_mul_f32 v[32:33], v[32:33], v[214:215]
	v_pk_mul_f32 v[34:35], v[34:35], v[216:217]
	v_pk_mul_f32 v[48:49], v[48:49], v[214:215]
	v_pk_mul_f32 v[50:51], v[50:51], v[216:217]
	ds_read_b128 v[214:217], v227 offset:32
	s_waitcnt lgkmcnt(0)
	v_pk_mul_f32 v[4:5], v[4:5], v[214:215]
	v_pk_mul_f32 v[6:7], v[6:7], v[216:217]
	v_pk_mul_f32 v[20:21], v[20:21], v[214:215]
	v_pk_mul_f32 v[22:23], v[22:23], v[216:217]
	v_pk_mul_f32 v[36:37], v[36:37], v[214:215]
	v_pk_mul_f32 v[38:39], v[38:39], v[216:217]
	v_pk_mul_f32 v[52:53], v[52:53], v[214:215]
	v_pk_mul_f32 v[54:55], v[54:55], v[216:217]
	ds_read_b128 v[214:217], v227 offset:64
	s_waitcnt lgkmcnt(0)
	v_pk_mul_f32 v[8:9], v[8:9], v[214:215]
	v_pk_mul_f32 v[10:11], v[10:11], v[216:217]
	v_pk_mul_f32 v[24:25], v[24:25], v[214:215]
	v_pk_mul_f32 v[26:27], v[26:27], v[216:217]
	v_pk_mul_f32 v[40:41], v[40:41], v[214:215]
	v_pk_mul_f32 v[42:43], v[42:43], v[216:217]
	v_pk_mul_f32 v[56:57], v[56:57], v[214:215]
	v_pk_mul_f32 v[58:59], v[58:59], v[216:217]
	ds_read_b128 v[214:217], v227 offset:96
	s_waitcnt lgkmcnt(0)
	v_pk_mul_f32 v[12:13], v[12:13], v[214:215]
	v_pk_mul_f32 v[14:15], v[14:15], v[216:217]
	v_pk_mul_f32 v[28:29], v[28:29], v[214:215]
	v_pk_mul_f32 v[30:31], v[30:31], v[216:217]
	v_pk_mul_f32 v[44:45], v[44:45], v[214:215]
	v_pk_mul_f32 v[46:47], v[46:47], v[216:217]
	v_pk_mul_f32 v[60:61], v[60:61], v[214:215]
	v_pk_mul_f32 v[62:63], v[62:63], v[216:217]

; __device__ __forceinline__ void cmask(f32x16&p0,f32x16&p1,int jb,int qrel,int hi){
;   const float NEG=-INFINITY; int kb=64*jb+4*hi;
;   #pragma unroll
;   for(int r=0;r<16;++r){int kv=kb+(r&3)+8*(r>>2); if(kv>qrel)p0[r]=NEG; if(kv+32>qrel)p1[r]=NEG;}
; }
.Lat_step_T1:
	v_add_u32_e32 v243, s16, v204
	ds_read_b64_tr_b16 v[214:215], v243 offset:24576
	ds_read_b64_tr_b16 v[216:217], v243 offset:25088
	v_mfma_f32_32x32x16_bf16 v[112:127], v[176:179], v[144:147], v[64:79]
	v_add_f32_e32 v245, v80, v81
	v_add_f32_e32 v245, v82, v245
	v_add_f32_e32 v245, v83, v245
	v_add_f32_e32 v245, v84, v245
	v_add_f32_e32 v245, v85, v245
	v_cvt_pk_bf16_f32 v160, v80, v81
	v_cvt_pk_bf16_f32 v161, v82, v83
	ds_read_b64_tr_b16 v[80:81], v243 offset:28672
	ds_read_b64_tr_b16 v[82:83], v243 offset:29184
	v_mfma_f32_32x32x16_bf16 v[128:143], v[180:183], v[144:147], v[64:79]
	v_add_f32_e32 v245, v86, v245
	v_add_f32_e32 v245, v87, v245
	v_add_f32_e32 v245, v88, v245
	v_add_f32_e32 v245, v89, v245
	v_cvt_pk_bf16_f32 v162, v84, v85
	v_cvt_pk_bf16_f32 v163, v86, v87
	ds_read_b64_tr_b16 v[84:85], v243 offset:25600
	ds_read_b64_tr_b16 v[86:87], v243 offset:26112
	v_mfma_f32_32x32x16_bf16 v[112:127], v[184:187], v[148:151], v[112:127]
	v_add_f32_e32 v245, v90, v245
	v_add_f32_e32 v245, v91, v245
	v_add_f32_e32 v245, v92, v245
	v_add_f32_e32 v245, v93, v245
	v_cvt_pk_bf16_f32 v164, v88, v89
	v_cvt_pk_bf16_f32 v165, v90, v91
	ds_read_b64_tr_b16 v[88:89], v243 offset:29696
	ds_read_b64_tr_b16 v[90:91], v243 offset:30208
	v_mfma_f32_32x32x16_bf16 v[128:143], v[188:191], v[148:151], v[128:143]
	v_add_f32_e32 v245, v94, v245
	v_add_f32_e32 v245, v95, v245
	v_add_f32_e32 v245, v96, v245
	v_add_f32_e32 v245, v97, v245
	v_cvt_pk_bf16_f32 v166, v92, v93
	v_cvt_pk_bf16_f32 v167, v94, v95
	ds_read_b64_tr_b16 v[92:93], v243 offset:26624
	ds_read_b64_tr_b16 v[94:95], v243 offset:27136
	v_mfma_f32_32x32x16_bf16 v[112:127], v[192:195], v[152:155], v[112:127]
	v_add_f32_e32 v245, v98, v245
	v_add_f32_e32 v245, v99, v245
	v_add_f32_e32 v245, v100, v245
	v_add_f32_e32 v245, v101, v245
	v_cvt_pk_bf16_f32 v168, v96, v97
	v_cvt_pk_bf16_f32 v169, v98, v99
	ds_read_b64_tr_b16 v[96:97], v243 offset:30720
	ds_read_b64_tr_b16 v[98:99], v243 offset:31232
	v_mfma_f32_32x32x16_bf16 v[128:143], v[196:199], v[152:155], v[128:143]
	v_add_f32_e32 v245, v102, v245
	v_add_f32_e32 v245, v103, v245
	v_add_f32_e32 v245, v104, v245
	v_add_f32_e32 v245, v105, v245
	v_cvt_pk_bf16_f32 v170, v100, v101
	v_cvt_pk_bf16_f32 v171, v102, v103
	ds_read_b64_tr_b16 v[100:101], v243 offset:27648
	ds_read_b64_tr_b16 v[102:103], v243 offset:28160
	v_mfma_f32_32x32x16_bf16 v[112:127], v[200:203], v[156:159], v[112:127]
	v_add_f32_e32 v245, v106, v245
	v_add_f32_e32 v245, v107, v245
	v_add_f32_e32 v245, v108, v245
	v_add_f32_e32 v245, v109, v245
	v_cvt_pk_bf16_f32 v172, v104, v105
	v_cvt_pk_bf16_f32 v173, v106, v107
	ds_read_b64_tr_b16 v[104:105], v243 offset:31744
	ds_read_b64_tr_b16 v[106:107], v243 offset:32256
	v_mfma_f32_32x32x16_bf16 v[128:143], v[206:209], v[156:159], v[128:143]
	v_add_f32_e32 v245, v110, v245
	v_add_f32_e32 v245, v111, v245
	v_cvt_pk_bf16_f32 v174, v108, v109
	v_cvt_pk_bf16_f32 v175, v110, v111
	v_add_f32_e32 v211, v211, v245
	s_waitcnt lgkmcnt(8)
	v_mfma_f32_32x32x16_bf16 v[0:15], v[160:163], v[214:217], v[0:15]
	v_add_u32_e32 v242, 0xffffff40, v225
	v_cmp_gt_i32_e64 s[28:29], 0, v242
	v_cmp_gt_i32_e64 s[30:31], 1, v242
	v_cmp_gt_i32_e64 s[34:35], 2, v242
	v_cndmask_b32_e64 v112, v112, v241, s[28:29]
	v_cmp_gt_i32_e64 s[28:29], 3, v242
	v_cndmask_b32_e64 v113, v113, v241, s[30:31]
	v_cmp_gt_i32_e64 s[30:31], 8, v242
	v_cndmask_b32_e64 v114, v114, v241, s[34:35]
	v_cmp_gt_i32_e64 s[34:35], 9, v242
	ds_read_b64_tr_b16 v[214:215], v243 offset:49152
	ds_read_b64_tr_b16 v[216:217], v243 offset:49664
	v_mfma_f32_32x32x16_bf16 v[16:31], v[160:163], v[80:83], v[16:31]
	v_cndmask_b32_e64 v115, v115, v241, s[28:29]
	v_cmp_gt_i32_e64 s[28:29], 10, v242
	v_cndmask_b32_e64 v116, v116, v241, s[30:31]
	v_cmp_gt_i32_e64 s[30:31], 11, v242
	v_cndmask_b32_e64 v117, v117, v241, s[34:35]
	v_cmp_gt_i32_e64 s[34:35], 16, v242
	v_cndmask_b32_e64 v118, v118, v241, s[28:29]
	v_cmp_gt_i32_e64 s[28:29], 17, v242
	v_cndmask_b32_e64 v119, v119, v241, s[30:31]
	v_cmp_gt_i32_e64 s[30:31], 18, v242
	ds_read_b64_tr_b16 v[80:81], v243 offset:53248
	ds_read_b64_tr_b16 v[82:83], v243 offset:53760
	v_mfma_f32_32x32x16_bf16 v[0:15], v[164:167], v[84:87], v[0:15]
	v_cndmask_b32_e64 v120, v120, v241, s[34:35]
	v_cmp_gt_i32_e64 s[34:35], 19, v242
	v_cndmask_b32_e64 v121, v121, v241, s[28:29]
	v_cmp_gt_i32_e64 s[28:29], 24, v242
	v_cndmask_b32_e64 v122, v122, v241, s[30:31]
	v_cmp_gt_i32_e64 s[30:31], 25, v242
	v_cndmask_b32_e64 v123, v123, v241, s[34:35]
	v_cmp_gt_i32_e64 s[34:35], 26, v242
	v_cndmask_b32_e64 v124, v124, v241, s[28:29]
	v_cmp_gt_i32_e64 s[28:29], 27, v242
	ds_read_b64_tr_b16 v[84:85], v243 offset:50176
	ds_read_b64_tr_b16 v[86:87], v243 offset:50688
	v_mfma_f32_32x32x16_bf16 v[16:31], v[164:167], v[88:91], v[16:31]
	v_cndmask_b32_e64 v125, v125, v241, s[30:31]
	v_cmp_gt_i32_e64 s[30:31], 32, v242
	v_cndmask_b32_e64 v126, v126, v241, s[34:35]
	v_cmp_gt_i32_e64 s[34:35], 33, v242
	v_cndmask_b32_e64 v127, v127, v241, s[28:29]
	v_cmp_gt_i32_e64 s[28:29], 34, v242
	v_cndmask_b32_e64 v128, v128, v241, s[30:31]
	v_cmp_gt_i32_e64 s[30:31], 35, v242
	v_cndmask_b32_e64 v129, v129, v241, s[34:35]
	v_cmp_gt_i32_e64 s[34:35], 40, v242
	ds_read_b64_tr_b16 v[88:89], v243 offset:54272
	ds_read_b64_tr_b16 v[90:91], v243 offset:54784
	s_waitcnt lgkmcnt(8)
; __device__ __forceinline__ void cmask(f32x16&p0,f32x16&p1,int jb,int qrel,int hi){
;   const float NEG=-INFINITY; int kb=64*jb+4*hi;
;   #pragma unroll
;   for(int r=0;r<16;++r){int kv=kb+(r&3)+8*(r>>2); if(kv>qrel)p0[r]=NEG; if(kv+32>qrel)p1[r]=NEG;}
; }
	v_mfma_f32_32x32x16_bf16 v[0:15], v[168:171], v[92:95], v[0:15]
	v_cndmask_b32_e64 v130, v130, v241, s[28:29]
	v_cmp_gt_i32_e64 s[28:29], 41, v242
	v_cndmask_b32_e64 v131, v131, v241, s[30:31]
	v_cmp_gt_i32_e64 s[30:31], 42, v242
	v_cndmask_b32_e64 v132, v132, v241, s[34:35]
	v_cmp_gt_i32_e64 s[34:35], 43, v242
	v_cndmask_b32_e64 v133, v133, v241, s[28:29]
	v_cmp_gt_i32_e64 s[28:29], 48, v242
	v_cndmask_b32_e64 v134, v134, v241, s[30:31]
	v_cmp_gt_i32_e64 s[30:31], 49, v242
	ds_read_b64_tr_b16 v[92:93], v243 offset:51200
	ds_read_b64_tr_b16 v[94:95], v243 offset:51712
	v_mfma_f32_32x32x16_bf16 v[16:31], v[168:171], v[96:99], v[16:31]
	v_cndmask_b32_e64 v135, v135, v241, s[34:35]
	v_cmp_gt_i32_e64 s[34:35], 50, v242
	v_cndmask_b32_e64 v136, v136, v241, s[28:29]
	v_cmp_gt_i32_e64 s[28:29], 51, v242
	v_cndmask_b32_e64 v137, v137, v241, s[30:31]
	v_cmp_gt_i32_e64 s[30:31], 56, v242
	v_cndmask_b32_e64 v138, v138, v241, s[34:35]
	v_cmp_gt_i32_e64 s[34:35], 57, v242
	v_cndmask_b32_e64 v139, v139, v241, s[28:29]
	v_cmp_gt_i32_e64 s[28:29], 58, v242
	ds_read_b64_tr_b16 v[96:97], v243 offset:55296
	ds_read_b64_tr_b16 v[98:99], v243 offset:55808
	v_mfma_f32_32x32x16_bf16 v[0:15], v[172:175], v[100:103], v[0:15]
	v_cndmask_b32_e64 v140, v140, v241, s[30:31]
	v_cmp_gt_i32_e64 s[30:31], 59, v242
	v_cndmask_b32_e64 v141, v141, v241, s[34:35]
	v_cndmask_b32_e64 v142, v142, v241, s[28:29]
	v_cndmask_b32_e64 v143, v143, v241, s[30:31]
	v_max3_f32 v246, v112, v113, v114
	v_max3_f32 v247, v115, v116, v117
	v_max3_f32 v246, v246, v118, v119
	v_max3_f32 v247, v247, v120, v121
	v_max3_f32 v246, v246, v122, v123
	ds_read_b64_tr_b16 v[100:101], v243 offset:52224
	ds_read_b64_tr_b16 v[102:103], v243 offset:52736
	v_mfma_f32_32x32x16_bf16 v[16:31], v[172:175], v[104:107], v[16:31]
	v_max3_f32 v247, v247, v124, v125
	v_max3_f32 v246, v246, v126, v127
	v_max3_f32 v247, v247, v128, v129
	v_max3_f32 v246, v246, v130, v131
	v_max3_f32 v247, v247, v132, v133
	v_max3_f32 v246, v246, v134, v135
	v_max3_f32 v247, v247, v136, v137
	v_max3_f32 v246, v246, v138, v139
	v_max3_f32 v247, v247, v140, v141
	v_max3_f32 v246, v246, v142, v143
	ds_read_b64_tr_b16 v[104:105], v243 offset:56320
	ds_read_b64_tr_b16 v[106:107], v243 offset:56832
	s_waitcnt lgkmcnt(8)
	v_mfma_f32_32x32x16_bf16 v[32:47], v[160:163], v[214:217], v[32:47]
	v_max_f32_e32 v248, v246, v247
	v_mov_b32_e32 v246, v248
	s_nop 1
	v_permlane32_swap_b32_e32 v248, v246
	v_max_f32_e32 v248, v248, v246
	v_cmp_lt_f32_e32 vcc, s87, v248
	s_cbranch_vccnz .Lat_rare_T1
.Lat_cont_T1:
	v_mfma_f32_32x32x16_bf16 v[48:63], v[160:163], v[80:83], v[48:63]
	v_exp_f32_e32 v112, v112
	v_exp_f32_e32 v113, v113
	v_exp_f32_e32 v114, v114
	v_exp_f32_e32 v115, v115
	v_exp_f32_e32 v116, v116
	v_mfma_f32_32x32x16_bf16 v[32:47], v[164:167], v[84:87], v[32:47]
	v_exp_f32_e32 v117, v117
	v_exp_f32_e32 v118, v118
	v_exp_f32_e32 v119, v119
	v_exp_f32_e32 v120, v120
	v_exp_f32_e32 v121, v121
	v_mfma_f32_32x32x16_bf16 v[48:63], v[164:167], v[88:91], v[48:63]
	v_exp_f32_e32 v122, v122
	v_exp_f32_e32 v123, v123
	v_exp_f32_e32 v124, v124
	v_exp_f32_e32 v125, v125
	v_exp_f32_e32 v126, v126
	s_waitcnt lgkmcnt(0)
	v_mfma_f32_32x32x16_bf16 v[32:47], v[168:171], v[92:95], v[32:47]
	v_exp_f32_e32 v127, v127
	v_exp_f32_e32 v128, v128
	v_exp_f32_e32 v129, v129
	v_exp_f32_e32 v130, v130
	v_exp_f32_e32 v131, v131
	v_mfma_f32_32x32x16_bf16 v[48:63], v[168:171], v[96:99], v[48:63]
	v_exp_f32_e32 v132, v132
	v_exp_f32_e32 v133, v133
	v_exp_f32_e32 v134, v134
	v_exp_f32_e32 v135, v135
	v_mfma_f32_32x32x16_bf16 v[32:47], v[172:175], v[100:103], v[32:47]
	v_exp_f32_e32 v136, v136
	v_exp_f32_e32 v137, v137
	v_exp_f32_e32 v138, v138
	v_exp_f32_e32 v139, v139
	v_mfma_f32_32x32x16_bf16 v[48:63], v[172:175], v[104:107], v[48:63]
	v_exp_f32_e32 v140, v140
	v_exp_f32_e32 v141, v141
	v_exp_f32_e32 v142, v142
	v_exp_f32_e32 v143, v143
	s_cbranch_vccz .Lat_noresc_T1
	s_waitcnt lgkmcnt(0)
	ds_read_b128 v[214:217], v227 offset:0
	s_waitcnt lgkmcnt(0)
	v_pk_mul_f32 v[0:1], v[0:1], v[214:215]
	v_pk_mul_f32 v[2:3], v[2:3], v[216:217]
	v_pk_mul_f32 v[16:17], v[16:17], v[214:215]
	v_pk_mul_f32 v[18:19], v[18:19], v[216:217]
	v_pk_mul_f32 v[32:33], v[32:33], v[214:215]
	v_pk_mul_f32 v[34:35], v[34:35], v[216:217]
	v_pk_mul_f32 v[48:49], v[48:49], v[214:215]
	v_pk_mul_f32 v[50:51], v[50:51], v[216:217]
	ds_read_b128 v[214:217], v227 offset:32
	s_waitcnt lgkmcnt(0)
	v_pk_mul_f32 v[4:5], v[4:5], v[214:215]
	v_pk_mul_f32 v[6:7], v[6:7], v[216:217]
	v_pk_mul_f32 v[20:21], v[20:21], v[214:215]
	v_pk_mul_f32 v[22:23], v[22:23], v[216:217]
	v_pk_mul_f32 v[36:37], v[36:37], v[214:215]
	v_pk_mul_f32 v[38:39], v[38:39], v[216:217]
	v_pk_mul_f32 v[52:53], v[52:53], v[214:215]
	v_pk_mul_f32 v[54:55], v[54:55], v[216:217]
	ds_read_b128 v[214:217], v227 offset:64
	s_waitcnt lgkmcnt(0)
	v_pk_mul_f32 v[8:9], v[8:9], v[214:215]
	v_pk_mul_f32 v[10:11], v[10:11], v[216:217]
	v_pk_mul_f32 v[24:25], v[24:25], v[214:215]
	v_pk_mul_f32 v[26:27], v[26:27], v[216:217]
	v_pk_mul_f32 v[40:41], v[40:41], v[214:215]
	v_pk_mul_f32 v[42:43], v[42:43], v[216:217]
	v_pk_mul_f32 v[56:57], v[56:57], v[214:215]
	v_pk_mul_f32 v[58:59], v[58:59], v[216:217]
	ds_read_b128 v[214:217], v227 offset:96
	s_waitcnt lgkmcnt(0)
	v_pk_mul_f32 v[12:13], v[12:13], v[214:215]
	v_pk_mul_f32 v[14:15], v[14:15], v[216:217]
	v_pk_mul_f32 v[28:29], v[28:29], v[214:215]
	v_pk_mul_f32 v[30:31], v[30:31], v[216:217]
	v_pk_mul_f32 v[44:45], v[44:45], v[214:215]
	v_pk_mul_f32 v[46:47], v[46:47], v[216:217]
	v_pk_mul_f32 v[60:61], v[60:61], v[214:215]
	v_pk_mul_f32 v[62:63], v[62:63], v[216:217]
; #define SBAR() __builtin_amdgcn_sched_barrier(0)
;   #define RESC() do{ if(resc){ asm volatile("s_waitcnt lgkmcnt(0)":::"memory"); \
;       _Pragma("unroll") for(int d_=0;d_<2;++d_) _Pragma("unroll") for(int r=0;r<16;++r)o[d_][r]*=wsf[crow(r,hi)]; } }while(0)
;   #define PKW(P,B) cvtpk_s(P[B],P[B+1])
; __device__ __forceinline__ void pv(f32x16*o,int vb,bf16x8 pa0,bf16x8 pa1,bf16x8 pa2,bf16x8 pa3){
;   #pragma unroll
;   for(int d0=0;d0<2;++d0){s16x4 lo[4],hi[4];
;     #pragma unroll
;     for(int ks=0;ks<4;++ks){
;       asm volatile("ds_read_b64_tr_b16 %0,%1 offset:%c2":"=&v"(lo[ks]):"v"(vb),"i"(d0*4096+ks*1024):"memory");
;       asm volatile("ds_read_b64_tr_b16 %0,%1 offset:%c2":"=&v"(hi[ks]):"v"(vb),"i"(d0*4096+ks*1024+512):"memory");}
;     asm volatile("s_waitcnt lgkmcnt(0)":::"memory");SBAR();
;     ...
;     o[d0]=__builtin_amdgcn_mfma_f32_32x32x16_bf16(pa0,PK(0),o[d0],0,0,0);
;     o[d0]=__builtin_amdgcn_mfma_f32_32x32x16_bf16(pa1,PK(1),o[d0],0,0,0);
;     o[d0]=__builtin_amdgcn_mfma_f32_32x32x16_bf16(pa2,PK(2),o[d0],0,0,0);
;     o[d0]=__builtin_amdgcn_mfma_f32_32x32x16_bf16(pa3,PK(3),o[d0],0,0,0);
;     ...
;   }
; }
; template<int THRL> __device__ __forceinline__ void attn_unit(int b,int qc,int vc,int qb,const bf16*Q,const bf16*__restrict__ K,const bf16*__restrict__ V,bf16*O,char*shm,const int tid){
;     ...
;   STEP(pB0,pB1,pA0,pA1,NT-1,false,false,false); RESC();
;   { float sacc=pB0[0]+pB0[1]; _Pragma("unroll") for(int r=2;r<16;++r)sacc+=pB0[r]; _Pragma("unroll") for(int r=0;r<16;++r)sacc+=pB1[r]; l_reg+=sacc;
;     pw0=(u32x4){PKW(pB0,0),PKW(pB0,2),PKW(pB0,4),PKW(pB0,6)};pw1=(u32x4){PKW(pB0,8),PKW(pB0,10),PKW(pB0,12),PKW(pB0,14)};pw2=(u32x4){PKW(pB1,0),PKW(pB1,2),PKW(pB1,4),PKW(pB1,6)};pw3=(u32x4){PKW(pB1,8),PKW(pB1,10),PKW(pB1,12),PKW(pB1,14)};
;     SBAR(); pv(o,vb0+sl_cur,PAF(0),PAF(1),PAF(2),PAF(3)); }
;     ...
;   {auto rr=__builtin_amdgcn_permlane32_swap(__float_as_uint(l_reg),__float_as_uint(l_reg),false,false);l_reg=__uint_as_float(rr[0])+__uint_as_float(rr[1]);}
;   if(hi==0)wsf[32+r32]=l_reg;asm volatile("s_waitcnt lgkmcnt(0)":::"memory");
.Lat_noresc_T1:
.Lat_drain:
	v_add_u32_e32 v243, s17, v204
	v_add_f32_e32 v245, v112, v113
	v_add_f32_e32 v245, v114, v245
	v_add_f32_e32 v245, v115, v245
	v_add_f32_e32 v245, v116, v245
	v_add_f32_e32 v245, v117, v245
	v_cvt_pk_bf16_f32 v160, v112, v113
	v_cvt_pk_bf16_f32 v161, v114, v115
	v_add_f32_e32 v245, v118, v245
	v_add_f32_e32 v245, v119, v245
	v_add_f32_e32 v245, v120, v245
	v_add_f32_e32 v245, v121, v245
	v_cvt_pk_bf16_f32 v162, v116, v117
	v_cvt_pk_bf16_f32 v163, v118, v119
	v_add_f32_e32 v245, v122, v245
	v_add_f32_e32 v245, v123, v245
	v_add_f32_e32 v245, v124, v245
	v_add_f32_e32 v245, v125, v245
	v_cvt_pk_bf16_f32 v164, v120, v121
	v_cvt_pk_bf16_f32 v165, v122, v123
	v_add_f32_e32 v245, v126, v245
	v_add_f32_e32 v245, v127, v245
	v_add_f32_e32 v245, v128, v245
	v_add_f32_e32 v245, v129, v245
	v_cvt_pk_bf16_f32 v166, v124, v125
	v_cvt_pk_bf16_f32 v167, v126, v127
	v_add_f32_e32 v245, v130, v245
	v_add_f32_e32 v245, v131, v245
	v_add_f32_e32 v245, v132, v245
	v_add_f32_e32 v245, v133, v245
	v_cvt_pk_bf16_f32 v168, v128, v129
	v_cvt_pk_bf16_f32 v169, v130, v131
	v_add_f32_e32 v245, v134, v245
	v_add_f32_e32 v245, v135, v245
	v_add_f32_e32 v245, v136, v245
	v_add_f32_e32 v245, v137, v245
	v_cvt_pk_bf16_f32 v170, v132, v133
	v_cvt_pk_bf16_f32 v171, v134, v135
	v_add_f32_e32 v245, v138, v245
	v_add_f32_e32 v245, v139, v245
	v_add_f32_e32 v245, v140, v245
	v_add_f32_e32 v245, v141, v245
	v_cvt_pk_bf16_f32 v172, v136, v137
	v_cvt_pk_bf16_f32 v173, v138, v139
	v_add_f32_e32 v245, v142, v245
	v_add_f32_e32 v245, v143, v245
	v_cvt_pk_bf16_f32 v174, v140, v141
	v_cvt_pk_bf16_f32 v175, v142, v143
	v_add_f32_e32 v211, v211, v245
	ds_read_b64_tr_b16 v[112:113], v243 offset:24576
	ds_read_b64_tr_b16 v[114:115], v243 offset:25088
	ds_read_b64_tr_b16 v[116:117], v243 offset:28672
	ds_read_b64_tr_b16 v[118:119], v243 offset:29184
	ds_read_b64_tr_b16 v[120:121], v243 offset:25600
	ds_read_b64_tr_b16 v[122:123], v243 offset:26112
	ds_read_b64_tr_b16 v[124:125], v243 offset:29696
	ds_read_b64_tr_b16 v[126:127], v243 offset:30208
	ds_read_b64_tr_b16 v[128:129], v243 offset:26624
	ds_read_b64_tr_b16 v[130:131], v243 offset:27136
	ds_read_b64_tr_b16 v[132:133], v243 offset:30720
	ds_read_b64_tr_b16 v[134:135], v243 offset:31232
	ds_read_b64_tr_b16 v[136:137], v243 offset:27648
	ds_read_b64_tr_b16 v[138:139], v243 offset:28160
	ds_read_b64_tr_b16 v[140:141], v243 offset:31744
	ds_read_b64_tr_b16 v[142:143], v243 offset:32256
	s_waitcnt lgkmcnt(14)
	v_mfma_f32_32x32x16_bf16 v[0:15], v[160:163], v[112:115], v[0:15]
	s_waitcnt lgkmcnt(12)
	v_mfma_f32_32x32x16_bf16 v[16:31], v[160:163], v[116:119], v[16:31]
	s_waitcnt lgkmcnt(10)
	v_mfma_f32_32x32x16_bf16 v[0:15], v[164:167], v[120:123], v[0:15]
	s_waitcnt lgkmcnt(8)
	v_mfma_f32_32x32x16_bf16 v[16:31], v[164:167], v[124:127], v[16:31]
	s_waitcnt lgkmcnt(6)
	v_mfma_f32_32x32x16_bf16 v[0:15], v[168:171], v[128:131], v[0:15]
	s_waitcnt lgkmcnt(4)
	v_mfma_f32_32x32x16_bf16 v[16:31], v[168:171], v[132:135], v[16:31]
	s_waitcnt lgkmcnt(2)
	v_mfma_f32_32x32x16_bf16 v[0:15], v[172:175], v[136:139], v[0:15]
	s_waitcnt lgkmcnt(0)
	v_mfma_f32_32x32x16_bf16 v[16:31], v[172:175], v[140:143], v[16:31]
	ds_read_b64_tr_b16 v[112:113], v243 offset:49152
	ds_read_b64_tr_b16 v[114:115], v243 offset:49664
	ds_read_b64_tr_b16 v[116:117], v243 offset:53248
	ds_read_b64_tr_b16 v[118:119], v243 offset:53760
	ds_read_b64_tr_b16 v[120:121], v243 offset:50176
	ds_read_b64_tr_b16 v[122:123], v243 offset:50688
	ds_read_b64_tr_b16 v[124:125], v243 offset:54272
	ds_read_b64_tr_b16 v[126:127], v243 offset:54784
	ds_read_b64_tr_b16 v[128:129], v243 offset:51200
	ds_read_b64_tr_b16 v[130:131], v243 offset:51712
	ds_read_b64_tr_b16 v[132:133], v243 offset:55296
	ds_read_b64_tr_b16 v[134:135], v243 offset:55808
	ds_read_b64_tr_b16 v[136:137], v243 offset:52224
	ds_read_b64_tr_b16 v[138:139], v243 offset:52736
	ds_read_b64_tr_b16 v[140:141], v243 offset:56320
	ds_read_b64_tr_b16 v[142:143], v243 offset:56832
	s_waitcnt lgkmcnt(14)
	v_mfma_f32_32x32x16_bf16 v[32:47], v[160:163], v[112:115], v[32:47]
	s_waitcnt lgkmcnt(12)
	v_mfma_f32_32x32x16_bf16 v[48:63], v[160:163], v[116:119], v[48:63]
	s_waitcnt lgkmcnt(10)
	v_mfma_f32_32x32x16_bf16 v[32:47], v[164:167], v[120:123], v[32:47]
	s_waitcnt lgkmcnt(8)
	v_mfma_f32_32x32x16_bf16 v[48:63], v[164:167], v[124:127], v[48:63]
	s_waitcnt lgkmcnt(6)
	v_mfma_f32_32x32x16_bf16 v[32:47], v[168:171], v[128:131], v[32:47]
	s_waitcnt lgkmcnt(4)
	v_mfma_f32_32x32x16_bf16 v[48:63], v[168:171], v[132:135], v[48:63]
	s_waitcnt lgkmcnt(2)
	v_mfma_f32_32x32x16_bf16 v[32:47], v[172:175], v[136:139], v[32:47]
	s_waitcnt lgkmcnt(0)
	v_mfma_f32_32x32x16_bf16 v[48:63], v[172:175], v[140:143], v[48:63]
	v_mov_b32_e32 v243, v211
	s_nop 1
	v_permlane32_swap_b32_e32 v211, v243
	v_add_f32_e32 v211, v211, v243
	ds_write_b32 v226, v211 offset:128
	s_waitcnt lgkmcnt(0)
	ds_read_b128 v[80:83], v227 offset:128
	ds_read_b128 v[84:87], v227 offset:160
	ds_read_b128 v[88:91], v227 offset:192
	ds_read_b128 v[92:95], v227 offset:224
	s_waitcnt lgkmcnt(0)
; __device__ __forceinline__ int crow(int r,int hi){return (r&3)+8*(r>>2)+4*hi;}
; template<int THRL> __device__ __forceinline__ void attn_unit(int b,int qc,int vc,int qb,const bf16*Q,const bf16*__restrict__ K,const bf16*__restrict__ V,bf16*O,char*shm,const int tid){
;     ...
;   float rli[16];
;   #pragma unroll
;   for(int r=0;r<16;++r)rli[r]=__builtin_amdgcn_rcpf(wsf[32+crow(r,hi)]);
;   bf16*Ow=O+(rowbase+q0+wid*QBLK)*DM+vc;
;   { bf16*stg=(bf16*)(shm+LDS_OST)+wid*2048;
;     #pragma unroll
;     for(int r=0;r<16;++r){const int orow=crow(r,hi);
;       #pragma unroll
;       for(int d0=0;d0<2;++d0)stg[orow*64+d0*32+r32]=__float2bfloat16(o[d0][r]*rli[r]);}
;     asm volatile("s_waitcnt lgkmcnt(0)":::"memory");
;     #pragma unroll
;     for(int i=0;i<4;++i){const int row=i*8+(lane>>3),ch=lane&7; const u32x4 v=*(const u32x4*)(stg+row*64+ch*8); ATTN_STORE16(Ow+(long)row*DM+ch*8,v);} }
	v_rcp_f32_e32 v80, v80
	v_rcp_f32_e32 v81, v81
	v_rcp_f32_e32 v82, v82
	v_rcp_f32_e32 v83, v83
	v_rcp_f32_e32 v84, v84
	v_rcp_f32_e32 v85, v85
	v_rcp_f32_e32 v86, v86
	v_rcp_f32_e32 v87, v87
	v_rcp_f32_e32 v88, v88
	v_rcp_f32_e32 v89, v89
	v_rcp_f32_e32 v90, v90
	v_rcp_f32_e32 v91, v91
	v_rcp_f32_e32 v92, v92
	v_rcp_f32_e32 v93, v93
	v_rcp_f32_e32 v94, v94
	v_rcp_f32_e32 v95, v95
	s_nop 0
	v_mul_f32_e32 v96, v0, v80
	v_cvt_pk_bf16_f32 v96, v96, v96
	ds_write_b16 v228, v96 offset:0
	v_mul_f32_e32 v97, v1, v81
	v_cvt_pk_bf16_f32 v97, v97, v97
	ds_write_b16 v228, v97 offset:128
	v_mul_f32_e32 v98, v2, v82
	v_cvt_pk_bf16_f32 v98, v98, v98
	ds_write_b16 v228, v98 offset:256
	v_mul_f32_e32 v99, v3, v83
	v_cvt_pk_bf16_f32 v99, v99, v99
	ds_write_b16 v228, v99 offset:384
	v_mul_f32_e32 v100, v4, v84
	v_cvt_pk_bf16_f32 v100, v100, v100
	ds_write_b16 v228, v100 offset:1024
	v_mul_f32_e32 v101, v5, v85
	v_cvt_pk_bf16_f32 v101, v101, v101
	ds_write_b16 v228, v101 offset:1152
	v_mul_f32_e32 v102, v6, v86
	v_cvt_pk_bf16_f32 v102, v102, v102
	ds_write_b16 v228, v102 offset:1280
	v_mul_f32_e32 v103, v7, v87
	v_cvt_pk_bf16_f32 v103, v103, v103
	ds_write_b16 v228, v103 offset:1408
	v_mul_f32_e32 v104, v8, v88
	v_cvt_pk_bf16_f32 v104, v104, v104
	ds_write_b16 v228, v104 offset:2048
	v_mul_f32_e32 v105, v9, v89
	v_cvt_pk_bf16_f32 v105, v105, v105
	ds_write_b16 v228, v105 offset:2176
	v_mul_f32_e32 v106, v10, v90
	v_cvt_pk_bf16_f32 v106, v106, v106
	ds_write_b16 v228, v106 offset:2304
	v_mul_f32_e32 v107, v11, v91
	v_cvt_pk_bf16_f32 v107, v107, v107
	ds_write_b16 v228, v107 offset:2432
	v_mul_f32_e32 v108, v12, v92
	v_cvt_pk_bf16_f32 v108, v108, v108
	ds_write_b16 v228, v108 offset:3072
	v_mul_f32_e32 v109, v13, v93
	v_cvt_pk_bf16_f32 v109, v109, v109
	ds_write_b16 v228, v109 offset:3200
	v_mul_f32_e32 v110, v14, v94
	v_cvt_pk_bf16_f32 v110, v110, v110
	ds_write_b16 v228, v110 offset:3328
	v_mul_f32_e32 v111, v15, v95
	v_cvt_pk_bf16_f32 v111, v111, v111
	ds_write_b16 v228, v111 offset:3456
	v_mul_f32_e32 v96, v16, v80
	v_cvt_pk_bf16_f32 v96, v96, v96
	ds_write_b16 v228, v96 offset:64
	v_mul_f32_e32 v97, v17, v81
	v_cvt_pk_bf16_f32 v97, v97, v97
	ds_write_b16 v228, v97 offset:192
	v_mul_f32_e32 v98, v18, v82
	v_cvt_pk_bf16_f32 v98, v98, v98
	ds_write_b16 v228, v98 offset:320
	v_mul_f32_e32 v99, v19, v83
	v_cvt_pk_bf16_f32 v99, v99, v99
	ds_write_b16 v228, v99 offset:448
	v_mul_f32_e32 v100, v20, v84
	v_cvt_pk_bf16_f32 v100, v100, v100
	ds_write_b16 v228, v100 offset:1088
	v_mul_f32_e32 v101, v21, v85
	v_cvt_pk_bf16_f32 v101, v101, v101
	ds_write_b16 v228, v101 offset:1216
	v_mul_f32_e32 v102, v22, v86
	v_cvt_pk_bf16_f32 v102, v102, v102
	ds_write_b16 v228, v102 offset:1344
	v_mul_f32_e32 v103, v23, v87
	v_cvt_pk_bf16_f32 v103, v103, v103
	ds_write_b16 v228, v103 offset:1472
	v_mul_f32_e32 v104, v24, v88
	v_cvt_pk_bf16_f32 v104, v104, v104
	ds_write_b16 v228, v104 offset:2112
	v_mul_f32_e32 v105, v25, v89
	v_cvt_pk_bf16_f32 v105, v105, v105
	ds_write_b16 v228, v105 offset:2240
	v_mul_f32_e32 v106, v26, v90
	v_cvt_pk_bf16_f32 v106, v106, v106
	ds_write_b16 v228, v106 offset:2368
	v_mul_f32_e32 v107, v27, v91
	v_cvt_pk_bf16_f32 v107, v107, v107
	ds_write_b16 v228, v107 offset:2496
	v_mul_f32_e32 v108, v28, v92
	v_cvt_pk_bf16_f32 v108, v108, v108
	ds_write_b16 v228, v108 offset:3136
	v_mul_f32_e32 v109, v29, v93
	v_cvt_pk_bf16_f32 v109, v109, v109
	ds_write_b16 v228, v109 offset:3264
	v_mul_f32_e32 v110, v30, v94
	v_cvt_pk_bf16_f32 v110, v110, v110
	ds_write_b16 v228, v110 offset:3392
	v_mul_f32_e32 v111, v31, v95
	v_cvt_pk_bf16_f32 v111, v111, v111
	ds_write_b16 v228, v111 offset:3520
	s_waitcnt lgkmcnt(0)
	ds_read_b128 v[112:115], v229 offset:0
	ds_read_b128 v[116:119], v229 offset:1024
	ds_read_b128 v[120:123], v229 offset:2048
	ds_read_b128 v[124:127], v229 offset:3072
	s_waitcnt lgkmcnt(3)
	v_mov_b32_e32 v243, v251
	global_store_dwordx4 v243, v[112:115], s[6:7] offset:0
	s_nop 1
	s_waitcnt lgkmcnt(2)
	v_add_u32_e32 v243, 0x4000, v243
	global_store_dwordx4 v243, v[116:119], s[6:7] offset:0
	s_nop 1
	s_waitcnt lgkmcnt(1)
	v_add_u32_e32 v243, 0x4000, v243
	global_store_dwordx4 v243, v[120:123], s[6:7] offset:0
	s_nop 1
	s_waitcnt lgkmcnt(0)
	v_add_u32_e32 v243, 0x4000, v243
	global_store_dwordx4 v243, v[124:127], s[6:7] offset:0
	s_nop 1
	v_mul_f32_e32 v96, v32, v80
	v_cvt_pk_bf16_f32 v96, v96, v96
	ds_write_b16 v228, v96 offset:0
	v_mul_f32_e32 v97, v33, v81
	v_cvt_pk_bf16_f32 v97, v97, v97
	ds_write_b16 v228, v97 offset:128
	v_mul_f32_e32 v98, v34, v82
	v_cvt_pk_bf16_f32 v98, v98, v98
	ds_write_b16 v228, v98 offset:256
	v_mul_f32_e32 v99, v35, v83
	v_cvt_pk_bf16_f32 v99, v99, v99
	ds_write_b16 v228, v99 offset:384
	v_mul_f32_e32 v100, v36, v84
	v_cvt_pk_bf16_f32 v100, v100, v100
	ds_write_b16 v228, v100 offset:1024
	v_mul_f32_e32 v101, v37, v85
	v_cvt_pk_bf16_f32 v101, v101, v101
	ds_write_b16 v228, v101 offset:1152
	v_mul_f32_e32 v102, v38, v86
	v_cvt_pk_bf16_f32 v102, v102, v102
	ds_write_b16 v228, v102 offset:1280
	v_mul_f32_e32 v103, v39, v87
	v_cvt_pk_bf16_f32 v103, v103, v103
	ds_write_b16 v228, v103 offset:1408
	v_mul_f32_e32 v104, v40, v88
	v_cvt_pk_bf16_f32 v104, v104, v104
	ds_write_b16 v228, v104 offset:2048
	v_mul_f32_e32 v105, v41, v89
	v_cvt_pk_bf16_f32 v105, v105, v105
	ds_write_b16 v228, v105 offset:2176
	v_mul_f32_e32 v106, v42, v90
	v_cvt_pk_bf16_f32 v106, v106, v106
	ds_write_b16 v228, v106 offset:2304
	v_mul_f32_e32 v107, v43, v91
	v_cvt_pk_bf16_f32 v107, v107, v107
	ds_write_b16 v228, v107 offset:2432
	v_mul_f32_e32 v108, v44, v92
	v_cvt_pk_bf16_f32 v108, v108, v108
	ds_write_b16 v228, v108 offset:3072
	v_mul_f32_e32 v109, v45, v93
; __device__ __forceinline__ int crow(int r,int hi){return (r&3)+8*(r>>2)+4*hi;}
; template<int THRL> __device__ __forceinline__ void attn_unit(int b,int qc,int vc,int qb,const bf16*Q,const bf16*__restrict__ K,const bf16*__restrict__ V,bf16*O,char*shm,const int tid){
;     ...
;     for(int r=0;r<16;++r){const int orow=crow(r,hi);
;       #pragma unroll
;       for(int d0=0;d0<2;++d0)stg[orow*64+d0*32+r32]=__float2bfloat16(o[d0][r]*rli[r]);}
;     asm volatile("s_waitcnt lgkmcnt(0)":::"memory");
;     #pragma unroll
;     for(int i=0;i<4;++i){const int row=i*8+(lane>>3),ch=lane&7; const u32x4 v=*(const u32x4*)(stg+row*64+ch*8); ATTN_STORE16(Ow+(long)row*DM+ch*8,v);} }
;   asm volatile("s_waitcnt lgkmcnt(0)\n\ts_barrier":::"memory");
	v_cvt_pk_bf16_f32 v109, v109, v109
	ds_write_b16 v228, v109 offset:3200
	v_mul_f32_e32 v110, v46, v94
	v_cvt_pk_bf16_f32 v110, v110, v110
	ds_write_b16 v228, v110 offset:3328
	v_mul_f32_e32 v111, v47, v95
	v_cvt_pk_bf16_f32 v111, v111, v111
	ds_write_b16 v228, v111 offset:3456
	v_mul_f32_e32 v96, v48, v80
	v_cvt_pk_bf16_f32 v96, v96, v96
	ds_write_b16 v228, v96 offset:64
	v_mul_f32_e32 v97, v49, v81
	v_cvt_pk_bf16_f32 v97, v97, v97
	ds_write_b16 v228, v97 offset:192
	v_mul_f32_e32 v98, v50, v82
	v_cvt_pk_bf16_f32 v98, v98, v98
	ds_write_b16 v228, v98 offset:320
	v_mul_f32_e32 v99, v51, v83
	v_cvt_pk_bf16_f32 v99, v99, v99
	ds_write_b16 v228, v99 offset:448
	v_mul_f32_e32 v100, v52, v84
	v_cvt_pk_bf16_f32 v100, v100, v100
	ds_write_b16 v228, v100 offset:1088
	v_mul_f32_e32 v101, v53, v85
	v_cvt_pk_bf16_f32 v101, v101, v101
	ds_write_b16 v228, v101 offset:1216
	v_mul_f32_e32 v102, v54, v86
	v_cvt_pk_bf16_f32 v102, v102, v102
	ds_write_b16 v228, v102 offset:1344
	v_mul_f32_e32 v103, v55, v87
	v_cvt_pk_bf16_f32 v103, v103, v103
	ds_write_b16 v228, v103 offset:1472
	v_mul_f32_e32 v104, v56, v88
	v_cvt_pk_bf16_f32 v104, v104, v104
	ds_write_b16 v228, v104 offset:2112
	v_mul_f32_e32 v105, v57, v89
	v_cvt_pk_bf16_f32 v105, v105, v105
	ds_write_b16 v228, v105 offset:2240
	v_mul_f32_e32 v106, v58, v90
	v_cvt_pk_bf16_f32 v106, v106, v106
	ds_write_b16 v228, v106 offset:2368
	v_mul_f32_e32 v107, v59, v91
	v_cvt_pk_bf16_f32 v107, v107, v107
	ds_write_b16 v228, v107 offset:2496
	v_mul_f32_e32 v108, v60, v92
	v_cvt_pk_bf16_f32 v108, v108, v108
	ds_write_b16 v228, v108 offset:3136
	v_mul_f32_e32 v109, v61, v93
	v_cvt_pk_bf16_f32 v109, v109, v109
	ds_write_b16 v228, v109 offset:3264
	v_mul_f32_e32 v110, v62, v94
	v_cvt_pk_bf16_f32 v110, v110, v110
	ds_write_b16 v228, v110 offset:3392
	v_mul_f32_e32 v111, v63, v95
	v_cvt_pk_bf16_f32 v111, v111, v111
	ds_write_b16 v228, v111 offset:3520
	s_waitcnt lgkmcnt(0)
	ds_read_b128 v[112:115], v229 offset:0
	ds_read_b128 v[116:119], v229 offset:1024
	ds_read_b128 v[120:123], v229 offset:2048
	ds_read_b128 v[124:127], v229 offset:3072
	s_waitcnt lgkmcnt(3)
	v_mov_b32_e32 v243, v251
	global_store_dwordx4 v243, v[112:115], s[6:7] offset:128
	s_nop 1
	s_waitcnt lgkmcnt(2)
	v_add_u32_e32 v243, 0x4000, v243
	global_store_dwordx4 v243, v[116:119], s[6:7] offset:128
	s_nop 1
	s_waitcnt lgkmcnt(1)
	v_add_u32_e32 v243, 0x4000, v243
	global_store_dwordx4 v243, v[120:123], s[6:7] offset:128
	s_nop 1
	s_waitcnt lgkmcnt(0)
	v_add_u32_e32 v243, 0x4000, v243
	global_store_dwordx4 v243, v[124:127], s[6:7] offset:128
	s_nop 1
	s_waitcnt lgkmcnt(0)
	s_barrier
	s_branch .Lat_unit_done
.Lat_rare_M1:
	v_max_f32_e32 v249, 0, v248
	v_exp_f32_e64 v250, -v249
	v_add_f32_e32 v210, v210, v249
	v_xor_b32_e32 v64, 0x80000000, v210
	v_mov_b32_e32 v65, v64
	v_mov_b32_e32 v66, v64
	v_mov_b32_e32 v67, v64
	v_mov_b32_e32 v68, v64
	v_mov_b32_e32 v69, v64
	v_mov_b32_e32 v70, v64
	v_mov_b32_e32 v71, v64
	v_mov_b32_e32 v72, v64
	v_mov_b32_e32 v73, v64
	v_mov_b32_e32 v74, v64
	v_mov_b32_e32 v75, v64
	v_mov_b32_e32 v76, v64
	v_mov_b32_e32 v77, v64
	v_mov_b32_e32 v78, v64
	v_mov_b32_e32 v79, v64
	ds_write_b32 v226, v250
	v_sub_f32_e32 v112, v112, v249
	v_sub_f32_e32 v113, v113, v249
	v_sub_f32_e32 v114, v114, v249
	v_sub_f32_e32 v115, v115, v249
	v_sub_f32_e32 v116, v116, v249
	v_sub_f32_e32 v117, v117, v249
	v_sub_f32_e32 v118, v118, v249
	v_sub_f32_e32 v119, v119, v249
	v_sub_f32_e32 v120, v120, v249
	v_sub_f32_e32 v121, v121, v249
	v_sub_f32_e32 v122, v122, v249
	v_sub_f32_e32 v123, v123, v249
	v_sub_f32_e32 v124, v124, v249
	v_sub_f32_e32 v125, v125, v249
	v_sub_f32_e32 v126, v126, v249
	v_sub_f32_e32 v127, v127, v249
	v_sub_f32_e32 v128, v128, v249
	v_sub_f32_e32 v129, v129, v249
	v_sub_f32_e32 v130, v130, v249
	v_sub_f32_e32 v131, v131, v249
	v_sub_f32_e32 v132, v132, v249
	v_sub_f32_e32 v133, v133, v249
	v_sub_f32_e32 v134, v134, v249
	v_sub_f32_e32 v135, v135, v249
	v_sub_f32_e32 v136, v136, v249
	v_sub_f32_e32 v137, v137, v249
	v_sub_f32_e32 v138, v138, v249
	v_sub_f32_e32 v139, v139, v249
	v_sub_f32_e32 v140, v140, v249
	v_sub_f32_e32 v141, v141, v249
	v_sub_f32_e32 v142, v142, v249
	v_sub_f32_e32 v143, v143, v249
	v_mul_f32_e32 v211, v211, v250
	s_branch .Lat_cont_M1
.Lat_rare_M2:
	v_max_f32_e32 v249, 0, v248
	v_exp_f32_e64 v250, -v249
	v_add_f32_e32 v210, v210, v249
	v_xor_b32_e32 v64, 0x80000000, v210
	v_mov_b32_e32 v65, v64
	v_mov_b32_e32 v66, v64
	v_mov_b32_e32 v67, v64
	v_mov_b32_e32 v68, v64
	v_mov_b32_e32 v69, v64
	v_mov_b32_e32 v70, v64
	v_mov_b32_e32 v71, v64
	v_mov_b32_e32 v72, v64
	v_mov_b32_e32 v73, v64
	v_mov_b32_e32 v74, v64
	v_mov_b32_e32 v75, v64
	v_mov_b32_e32 v76, v64
	v_mov_b32_e32 v77, v64
	v_mov_b32_e32 v78, v64
	v_mov_b32_e32 v79, v64
	ds_write_b32 v226, v250
	v_sub_f32_e32 v80, v80, v249
	v_sub_f32_e32 v81, v81, v249
	v_sub_f32_e32 v82, v82, v249
	v_sub_f32_e32 v83, v83, v249
	v_sub_f32_e32 v84, v84, v249
	v_sub_f32_e32 v85, v85, v249
	v_sub_f32_e32 v86, v86, v249
	v_sub_f32_e32 v87, v87, v249
	v_sub_f32_e32 v88, v88, v249
	v_sub_f32_e32 v89, v89, v249
	v_sub_f32_e32 v90, v90, v249
	v_sub_f32_e32 v91, v91, v249
	v_sub_f32_e32 v92, v92, v249
	v_sub_f32_e32 v93, v93, v249
	v_sub_f32_e32 v94, v94, v249
	v_sub_f32_e32 v95, v95, v249
	v_sub_f32_e32 v96, v96, v249
	v_sub_f32_e32 v97, v97, v249
	v_sub_f32_e32 v98, v98, v249
	v_sub_f32_e32 v99, v99, v249
	v_sub_f32_e32 v100, v100, v249
	v_sub_f32_e32 v101, v101, v249
	v_sub_f32_e32 v102, v102, v249
	v_sub_f32_e32 v103, v103, v249
	v_sub_f32_e32 v104, v104, v249
	v_sub_f32_e32 v105, v105, v249
	v_sub_f32_e32 v106, v106, v249
	v_sub_f32_e32 v107, v107, v249
	v_sub_f32_e32 v108, v108, v249
	v_sub_f32_e32 v109, v109, v249
	v_sub_f32_e32 v110, v110, v249
	v_sub_f32_e32 v111, v111, v249
	v_mul_f32_e32 v211, v211, v250
	s_branch .Lat_cont_M2
